# attention ping-pong loop: frozen-reference softmax fast path (Q pre-scaled in f32), K fragment prefetch 4 steps deep
# speedup vs baseline: 1.0637x; 1.0218x over previous
; __device__ __forceinline__ void unpack8(const u32x4 w, float* f) { f[0] = bf_lo(w.x); f[1] = bf_hi(w.x); f[2] = bf_lo(w.y); f[3] = bf_hi(w.y); f[4] = bf_lo(w.z); f[5] = bf_hi(w.z); f[6] = bf_lo(w.w); f[7] = bf_hi(w.w); }
; __device__ __forceinline__ void attn_unit(const bf16_t* __restrict__ Qb, const bf16_t* __restrict__ KV, const bf16_t* __restrict__ KP, bf16_t* __restrict__ Ob, ...
;   int tid_ = threadIdx.x; asm volatile("" : "+v"(tid_));
;   const int tid = tid_, wid = tid >> 6, lane = tid & 63, r32 = lane & 31, hi = lane >> 5;
;   char* V_lds = lds + OFF_V; char* KN_lds = lds + OFF_KN; char* KP_lds = lds + OFF_KP;
;   float* ws = (float*)(lds + OFF_WS) + wid * 64; float* li_l = ws; float* al_l = ws + 32;
;   float m_reg = -1e30f, l_reg = 0; f32x16 o[4] = {}; bf16x8 qr[12];
;   const bf16_t* Qw = Qb + (size_t)(qrow0 + wid * QBLK + r32) * LDQ + h * QKD + hi * 8;
; #pragma unroll
;   for (int d0 = 0; d0 < 12; ++d0) qr[d0] = ld8(Qw + d0 * 16);
;   {
;     float qf[12][8]; float ss = 0.f;
; #pragma unroll
;     for (int d0 = 0; d0 < 12; ++d0) { const u32x4 w = *reinterpret_cast<const u32x4*>(&qr[d0]); unpack8(w, qf[d0]);
; #pragma unroll
;       for (int jj = 0; jj < 8; ++jj) ss += qf[d0][jj] * qf[d0][jj]; }
;     { auto rr = __builtin_amdgcn_permlane32_swap(__float_as_uint(ss), __float_as_uint(ss), false, false); ss = __uint_as_float(rr[0]) + __uint_as_float(rr[1]); }
;     const float rinv = 1.0f / sqrtf(ss * (1.f / QKD) + EPS);
.LBB0_1452:
	s_ashr_i32 s8, s2, 7
	s_lshl_b32 s6, s2, 8
	v_mov_b32_e32 v162, v188
	s_lshl_b32 s24, s8, 12
	s_and_b32 s6, s6, 0xf00
	s_or_b32 s6, s24, s6
	v_ashrrev_i32_e32 v0, 1, v162
	v_and_b32_e32 v0, 0xffffffe0, v0
	v_and_b32_e32 v184, 31, v162
	v_add_u32_e32 v178, s6, v0
	s_bfe_u32 s3, s2, 0x30004
	v_or_b32_e32 v36, v178, v184
	v_mov_b64_e32 v[0:1], s[14:15]
	v_bfe_u32 v185, v162, 5, 1
	v_mad_i64_i32 v[0:1], s[6:7], v36, s89, v[0:1]
	s_mul_i32 s68, s3, 0x180
	v_lshl_add_u64 v[0:1], v[0:1], 0, s[68:69]
	v_lshlrev_b32_e32 v172, 4, v185
	v_lshl_add_u64 v[32:33], v[0:1], 0, v[172:173]
	global_load_dwordx4 v[20:23], v[32:33], off
	global_load_dwordx4 v[24:27], v[32:33], off offset:32
	global_load_dwordx4 v[16:19], v[32:33], off offset:64
	global_load_dwordx4 v[12:15], v[32:33], off offset:96
	global_load_dwordx4 v[8:11], v[32:33], off offset:128
	global_load_dwordx4 v[4:7], v[32:33], off offset:160
	global_load_dwordx4 v[0:3], v[32:33], off offset:192
	v_and_b32_e32 v124, 32, v162
	global_load_dwordx4 v[112:115], v124, s[20:21] offset:704
	global_load_dwordx4 v[138:141], v124, s[20:21] offset:720
	global_load_dwordx4 v[28:31], v[32:33], off offset:224
	global_load_dwordx4 v[100:103], v[32:33], off offset:256
	global_load_dwordx4 v[96:99], v[32:33], off offset:288
	global_load_dwordx4 v[116:119], v[32:33], off offset:320
	global_load_dwordx4 v[120:123], v[32:33], off offset:352
	v_mov_b32_e32 v125, v173
	s_mov_b64 s[6:7], 0x1000
	s_lshl_b32 s25, s8, 8
	s_add_i32 s11, 0, 0x14000
	s_add_i32 s31, s25, 0x4000
	s_cmp_lg_u32 0, -1
	s_cselect_b32 s34, 0, 0
	s_mov_b32 s50, s48
	s_mov_b32 s51, s48
	s_mov_b32 s52, s48
	s_mov_b32 s53, s48
	s_mov_b32 s54, s48
	s_mov_b32 s55, s48
	s_mov_b32 s56, s48
	s_mov_b32 s57, s48
	s_mov_b32 s58, s48
	s_mov_b32 s59, s48
	s_mov_b32 s60, s48
	s_mov_b32 s61, s48
	s_mov_b32 s62, s48
	s_mov_b32 s63, s48
	v_mov_b64_e32 v[190:191], 0x100
	v_mov_b64_e32 v[252:253], 0xff
	s_waitcnt vmcnt(0)
	v_lshlrev_b32_e32 v229, 16, v20
	v_and_b32_e32 v230, 0xffff0000, v20
	v_lshlrev_b32_e32 v214, 16, v16
	v_and_b32_e32 v213, 0xffff0000, v16
	v_lshlrev_b32_e32 v212, 16, v17
	v_and_b32_e32 v211, 0xffff0000, v17
	v_lshlrev_b32_e32 v210, 16, v18
	v_and_b32_e32 v209, 0xffff0000, v18
	v_lshlrev_b32_e32 v208, 16, v19
	v_and_b32_e32 v207, 0xffff0000, v19
	global_load_dwordx4 v[16:19], v124, s[20:21] offset:656
	v_lshlrev_b32_e32 v227, 16, v21
	v_and_b32_e32 v228, 0xffff0000, v21
	v_lshlrev_b32_e32 v225, 16, v22
	v_and_b32_e32 v226, 0xffff0000, v22
	v_lshlrev_b32_e32 v223, 16, v23
	v_and_b32_e32 v224, 0xffff0000, v23
	global_load_dwordx4 v[20:23], v124, s[20:21] offset:640
	v_mul_f32_e32 v194, v230, v230
	v_fmac_f32_e32 v194, v229, v229
	v_fmac_f32_e32 v194, v227, v227
	v_fmac_f32_e32 v194, v228, v228
	v_fmac_f32_e32 v194, v225, v225
	v_fmac_f32_e32 v194, v226, v226
	v_fmac_f32_e32 v194, v223, v223
	v_lshlrev_b32_e32 v221, 16, v24
	v_fmac_f32_e32 v194, v224, v224
	v_and_b32_e32 v222, 0xffff0000, v24
	v_fmac_f32_e32 v194, v221, v221
	v_lshlrev_b32_e32 v219, 16, v25
	v_fmac_f32_e32 v194, v222, v222
	v_and_b32_e32 v220, 0xffff0000, v25
	v_fmac_f32_e32 v194, v219, v219
	v_lshlrev_b32_e32 v218, 16, v26
	v_fmac_f32_e32 v194, v220, v220
	v_and_b32_e32 v217, 0xffff0000, v26
	v_fmac_f32_e32 v194, v218, v218
	v_lshlrev_b32_e32 v216, 16, v27
	v_fmac_f32_e32 v194, v217, v217
	v_and_b32_e32 v215, 0xffff0000, v27
	v_fmac_f32_e32 v194, v216, v216
	v_fmac_f32_e32 v194, v215, v215
	v_fmac_f32_e32 v194, v214, v214
	v_fmac_f32_e32 v194, v213, v213
	v_fmac_f32_e32 v194, v212, v212
	v_fmac_f32_e32 v194, v211, v211
	v_fmac_f32_e32 v194, v210, v210
	v_lshlrev_b32_e32 v165, 16, v0
	v_and_b32_e32 v164, 0xffff0000, v0
	v_fmac_f32_e32 v194, v209, v209
	v_lshlrev_b32_e32 v0, 6, v36
	v_lshlrev_b32_e32 v163, 16, v1
	v_fmac_f32_e32 v194, v208, v208
	v_and_b32_e32 v239, 0xffff0000, v1
	v_lshl_add_u64 v[24:25], s[18:19], 0, v[124:125]
	v_and_b32_e32 v0, 0xfc0, v0
	v_mov_b32_e32 v1, v173
	v_lshlrev_b32_e32 v206, 16, v12
	v_lshlrev_b32_e32 v180, 16, v4
	v_and_b32_e32 v179, 0xffff0000, v4
	v_lshlrev_b32_e32 v171, 16, v5
	v_and_b32_e32 v170, 0xffff0000, v5
	v_fmac_f32_e32 v194, v207, v207
	v_lshl_add_u64 v[4:5], v[24:25], 0, v[0:1]
	v_and_b32_e32 v205, 0xffff0000, v12
	v_lshlrev_b32_e32 v198, 16, v8
	v_and_b32_e32 v197, 0xffff0000, v8
	v_lshlrev_b32_e32 v196, 16, v9
	v_and_b32_e32 v187, 0xffff0000, v9
	v_lshlrev_b32_e32 v186, 16, v10
	v_and_b32_e32 v183, 0xffff0000, v10
	v_lshlrev_b32_e32 v182, 16, v11
	v_and_b32_e32 v181, 0xffff0000, v11
	v_lshlrev_b32_e32 v169, 16, v6
	v_and_b32_e32 v168, 0xffff0000, v6
	v_lshlrev_b32_e32 v167, 16, v7
	v_and_b32_e32 v166, 0xffff0000, v7
	v_fmac_f32_e32 v194, v206, v206
	v_lshlrev_b32_e32 v237, 16, v2
	v_and_b32_e32 v235, 0xffff0000, v2
	v_lshlrev_b32_e32 v233, 16, v3
	v_and_b32_e32 v231, 0xffff0000, v3
	global_load_dwordx4 v[104:107], v124, s[20:21] offset:16
	global_load_dwordx4 v[108:111], v124, s[20:21]
	global_load_dwordx4 v[88:91], v124, s[20:21] offset:80
	global_load_dwordx4 v[92:95], v124, s[20:21] offset:64
	global_load_dwordx4 v[80:83], v124, s[20:21] offset:144
	global_load_dwordx4 v[84:87], v124, s[20:21] offset:128
	global_load_dwordx4 v[72:75], v124, s[20:21] offset:208
	global_load_dwordx4 v[76:79], v124, s[20:21] offset:192
	global_load_dwordx4 v[64:67], v124, s[20:21] offset:272
	global_load_dwordx4 v[68:71], v124, s[20:21] offset:256
	global_load_dwordx4 v[48:51], v124, s[20:21] offset:336
	global_load_dwordx4 v[56:59], v124, s[20:21] offset:320
	global_load_dwordx4 v[32:35], v124, s[20:21] offset:400
	global_load_dwordx4 v[40:43], v124, s[20:21] offset:384
	global_load_dwordx4 v[8:11], v[4:5], off
	global_load_dwordx4 v[0:3], v[4:5], off offset:16
; __device__ __forceinline__ void unpack8(const u32x4 w, float* f) { f[0] = bf_lo(w.x); f[1] = bf_hi(w.x); f[2] = bf_lo(w.y); f[3] = bf_hi(w.y); f[4] = bf_lo(w.z); f[5] = bf_hi(w.z); f[6] = bf_lo(w.w); f[7] = bf_hi(w.w); }
; __device__ __forceinline__ void attn_unit(const bf16_t* __restrict__ Qb, const bf16_t* __restrict__ KV, const bf16_t* __restrict__ KP, bf16_t* __restrict__ Ob, ...
;     ...
;     for (int d0 = 0; d0 < 12; ++d0) { const u32x4 w = *reinterpret_cast<const u32x4*>(&qr[d0]); unpack8(w, qf[d0]);
; #pragma unroll
;       for (int jj = 0; jj < 8; ++jj) ss += qf[d0][jj] * qf[d0][jj]; }
;     { auto rr = __builtin_amdgcn_permlane32_swap(__float_as_uint(ss), __float_as_uint(ss), false, false); ss = __uint_as_float(rr[0]) + __uint_as_float(rr[1]); }
;     const float rinv = 1.0f / sqrtf(ss * (1.f / QKD) + EPS);
; #pragma unroll
;     for (int d0 = 0; d0 < 12; ++d0) { const f32x4 g0 = *(const f32x4*)(qn + d0 * 16 + hi * 8), g1 = *(const f32x4*)(qn + d0 * 16 + hi * 8 + 4);
; #pragma unroll
;       for (int jj = 0; jj < 8; ++jj) qf[d0][jj] *= rinv * (jj < 4 ? g0[jj & 3] : g1[jj & 3]); }
;     if (do_rope) { const int s = (qrow0 + wid * QBLK + r32) & (SEQ - 1), pr_ = s >> 6, pc_ = s & 63;
; #pragma unroll
;       for (int ax = 0; ax < 2; ++ax) { const float* cp = rope + (ax ? pc_ : pr_) * 16 + hi * 8; const f32x4 c0 = *(const f32x4*)cp, c1 = *(const f32x4*)(cp + 4), s0 = *(const f32x4*)(cp + 1024), s1 = *(const f32x4*)(cp + 1028);
	v_lshl_add_u64 v[6:7], v[4:5], 0, s[6:7]
	v_add_co_u32_e32 v4, vcc, s49, v4
	v_lshlrev_b32_e32 v204, 16, v13
	v_fmac_f32_e32 v194, v205, v205
	v_addc_co_u32_e32 v5, vcc, 0, v5, vcc
	v_and_b32_e32 v203, 0xffff0000, v13
	v_lshlrev_b32_e32 v202, 16, v14
	v_and_b32_e32 v201, 0xffff0000, v14
	v_lshlrev_b32_e32 v200, 16, v15
	v_and_b32_e32 v199, 0xffff0000, v15
	v_fmac_f32_e32 v194, v204, v204
	v_lshlrev_b32_e32 v241, 16, v28
	v_and_b32_e32 v244, 0xffff0000, v28
	v_lshlrev_b32_e32 v245, 16, v29
	v_and_b32_e32 v240, 0xffff0000, v29
	v_lshlrev_b32_e32 v238, 16, v30
	v_and_b32_e32 v236, 0xffff0000, v30
	v_lshlrev_b32_e32 v234, 16, v31
	v_and_b32_e32 v232, 0xffff0000, v31
	global_load_dwordx4 v[12:15], v[4:5], off
	s_nop 0
	global_load_dwordx4 v[4:7], v[6:7], off offset:16
	s_nop 0
	global_load_dwordx4 v[52:55], v124, s[20:21] offset:464
	global_load_dwordx4 v[60:63], v124, s[20:21] offset:448
	global_load_dwordx4 v[36:39], v124, s[20:21] offset:512
	global_load_dwordx4 v[28:31], v124, s[20:21] offset:528
	global_load_dwordx4 v[44:47], v124, s[20:21] offset:576
	s_nop 0
	global_load_dwordx4 v[124:127], v124, s[20:21] offset:592
	v_fmac_f32_e32 v194, v203, v203
	v_fmac_f32_e32 v194, v202, v202
	v_fmac_f32_e32 v194, v201, v201
	v_fmac_f32_e32 v194, v200, v200
	v_fmac_f32_e32 v194, v199, v199
	v_fmac_f32_e32 v194, v198, v198
	v_fmac_f32_e32 v194, v197, v197
	v_fmac_f32_e32 v194, v196, v196
	v_fmac_f32_e32 v194, v187, v187
	v_fmac_f32_e32 v194, v186, v186
	v_fmac_f32_e32 v194, v183, v183
	v_fmac_f32_e32 v194, v182, v182
	v_fmac_f32_e32 v194, v181, v181
	v_fmac_f32_e32 v194, v180, v180
	v_fmac_f32_e32 v194, v179, v179
	v_fmac_f32_e32 v194, v171, v171
	v_fmac_f32_e32 v194, v170, v170
	v_fmac_f32_e32 v194, v169, v169
	v_fmac_f32_e32 v194, v168, v168
	v_fmac_f32_e32 v194, v167, v167
	v_fmac_f32_e32 v194, v166, v166
	v_fmac_f32_e32 v194, v165, v165
	v_fmac_f32_e32 v194, v164, v164
	v_fmac_f32_e32 v194, v163, v163
	v_fmac_f32_e32 v194, v239, v239
	v_fmac_f32_e32 v194, v237, v237
	v_fmac_f32_e32 v194, v235, v235
	v_fmac_f32_e32 v194, v233, v233
	v_fmac_f32_e32 v194, v231, v231
	v_fmac_f32_e32 v194, v241, v241
	v_fmac_f32_e32 v194, v244, v244
	v_fmac_f32_e32 v194, v245, v245
	v_fmac_f32_e32 v194, v240, v240
	v_fmac_f32_e32 v194, v238, v238
	v_fmac_f32_e32 v194, v236, v236
	v_fmac_f32_e32 v194, v234, v234
	v_lshlrev_b32_e32 v159, 16, v100
	v_lshlrev_b32_e32 v158, 16, v96
	v_fmac_f32_e32 v194, v232, v232
	v_lshlrev_b32_e32 v154, 16, v97
	v_and_b32_e32 v156, 0xffff0000, v97
	v_and_b32_e32 v161, 0xffff0000, v100
	v_and_b32_e32 v160, 0xffff0000, v96
	v_pk_mul_f32 v[96:97], v[158:159], v[158:159]
	v_lshlrev_b32_e32 v146, 16, v99
	v_and_b32_e32 v148, 0xffff0000, v99
	v_lshlrev_b32_e32 v150, 16, v98
	v_and_b32_e32 v152, 0xffff0000, v98
	v_lshlrev_b32_e32 v155, 16, v101
	v_add_f32_e32 v97, v97, v194
	v_pk_mul_f32 v[98:99], v[160:161], v[160:161]
	v_pk_mul_f32 v[192:193], v[154:155], v[154:155]
	v_and_b32_e32 v157, 0xffff0000, v101
	v_add_f32_e32 v97, v99, v97
	v_lshlrev_b32_e32 v151, 16, v102
	v_pk_mul_f32 v[100:101], v[156:157], v[156:157]
	v_add_f32_e32 v97, v193, v97
	v_lshlrev_b32_e32 v128, 16, v123
	v_lshlrev_b32_e32 v129, 16, v119
	v_mov_b32_e32 v130, v140
	s_waitcnt vmcnt(25)
	v_mov_b32_e32 v131, v18
	v_and_b32_e32 v133, 0xffff0000, v119
	v_and_b32_e32 v132, 0xffff0000, v123
	v_mov_b32_e32 v18, v141
	v_lshlrev_b32_e32 v135, 16, v118
	v_lshlrev_b32_e32 v134, 16, v122
	v_and_b32_e32 v119, 0xffff0000, v118
	v_and_b32_e32 v118, 0xffff0000, v122
	v_lshlrev_b32_e32 v123, 16, v117
	v_lshlrev_b32_e32 v122, 16, v121
	v_and_b32_e32 v141, 0xffff0000, v117
	v_and_b32_e32 v140, 0xffff0000, v121
	v_lshlrev_b32_e32 v143, 16, v116
	v_lshlrev_b32_e32 v142, 16, v120
	v_and_b32_e32 v117, 0xffff0000, v116
	v_and_b32_e32 v116, 0xffff0000, v120
	v_pk_mul_f32 v[120:121], v[150:151], v[150:151]
	v_and_b32_e32 v153, 0xffff0000, v102
	v_add_f32_e32 v97, v101, v97
	v_lshlrev_b32_e32 v147, 16, v103
	v_and_b32_e32 v149, 0xffff0000, v103
	v_pk_mul_f32 v[102:103], v[152:153], v[152:153]
	v_add_f32_e32 v97, v121, v97
	v_mov_b32_e32 v144, v112
	s_waitcnt vmcnt(24)
	v_mov_b32_e32 v145, v20
	v_mov_b32_e32 v20, v113
	v_pk_mul_f32 v[112:113], v[146:147], v[146:147]
	v_add_f32_e32 v97, v103, v97
	v_mov_b32_e32 v136, v138
	v_mov_b32_e32 v137, v16
	v_mov_b32_e32 v16, v139
	v_mov_b32_e32 v138, v114
	v_mov_b32_e32 v139, v22
	v_mov_b32_e32 v22, v115
	v_pk_mul_f32 v[114:115], v[148:149], v[148:149]
	v_add_f32_e32 v97, v113, v97
	v_add_f32_e32 v97, v115, v97
	v_add_f32_e32 v96, v96, v97
	v_add_f32_e32 v101, v98, v96
	v_add_f32_e32 v101, v192, v101
	v_add_f32_e32 v100, v100, v101
	v_add_f32_e32 v100, v120, v100
	v_add_f32_e32 v100, v102, v100
	v_add_f32_e32 v102, v112, v100
	v_pk_mul_f32 v[100:101], v[142:143], v[142:143]
	v_add_f32_e32 v102, v114, v102
	v_and_b32_e32 v26, 0xfc0, v178
	v_mov_b32_e32 v27, v173
	v_pk_mul_f32 v[112:113], v[116:117], v[116:117]
	v_add_f32_e32 v101, v101, v102
	v_lshl_add_u64 v[174:175], v[24:25], 0, v[26:27]
	v_pk_mul_f32 v[120:121], v[122:123], v[122:123]
	v_add_f32_e32 v101, v113, v101
	v_lshl_add_u64 v[176:177], v[174:175], 0, s[6:7]
	v_pk_mul_f32 v[242:243], v[140:141], v[140:141]
	v_add_f32_e32 v101, v121, v101
	global_load_dwordx4 v[96:99], v[176:177], off offset:16
	v_pk_mul_f32 v[176:177], v[134:135], v[134:135]
	v_add_f32_e32 v101, v243, v101
	v_pk_mul_f32 v[192:193], v[118:119], v[118:119]
	v_add_f32_e32 v101, v177, v101
	v_add_f32_e32 v101, v193, v101
	v_fmac_f32_e32 v101, v129, v129
	v_fmac_f32_e32 v101, v133, v133
	v_add_f32_e32 v113, v100, v101
	v_add_f32_e32 v121, v112, v113
	global_load_dwordx4 v[24:27], v[174:175], off offset:16
	global_load_dwordx4 v[100:103], v[174:175], off
	v_add_co_u32_e32 v194, vcc, s49, v174
	v_add_f32_e32 v174, v120, v121
	s_nop 0
	v_addc_co_u32_e32 v195, vcc, 0, v175, vcc
	v_add_f32_e32 v177, v242, v174
	global_load_dwordx4 v[112:115], v[194:195], off
	v_mov_b32_e32 v174, v132
	v_mov_b32_e32 v175, v128
	v_add_f32_e32 v176, v176, v177
	v_pk_mul_f32 v[174:175], v[174:175], v[174:175]
	v_add_f32_e32 v176, v192, v176
	v_add_f32_e32 v175, v175, v176
	v_add_f32_e32 v174, v174, v175
	v_mov_b32_e32 v175, v174
	s_nop 1
	v_permlane32_swap_b32_e32 v174, v175
	v_add_f32_e32 v174, v174, v175
	v_fmamk_f32 v174, v174, 0x3baaaaab, v189
	v_mul_f32_e32 v175, 0x4f800000, v174
	v_cmp_gt_f32_e32 vcc, s91, v174
	s_waitcnt vmcnt(12)
; __device__ __forceinline__ void attn_unit(const bf16_t* __restrict__ Qb, const bf16_t* __restrict__ KV, const bf16_t* __restrict__ KP, bf16_t* __restrict__ Ob, ...
;     ...
;     { auto rr = __builtin_amdgcn_permlane32_swap(__float_as_uint(ss), __float_as_uint(ss), false, false); ss = __uint_as_float(rr[0]) + __uint_as_float(rr[1]); }
;     const float rinv = 1.0f / sqrtf(ss * (1.f / QKD) + EPS);
; #pragma unroll
;     for (int d0 = 0; d0 < 12; ++d0) { const f32x4 g0 = *(const f32x4*)(qn + d0 * 16 + hi * 8), g1 = *(const f32x4*)(qn + d0 * 16 + hi * 8 + 4);
; #pragma unroll
;       for (int jj = 0; jj < 8; ++jj) qf[d0][jj] *= rinv * (jj < 4 ? g0[jj & 3] : g1[jj & 3]); }
	v_mov_b32_e32 v120, v2
	s_waitcnt vmcnt(10)
	v_mov_b32_e32 v121, v6
	v_cndmask_b32_e32 v176, v174, v175, vcc
	v_sqrt_f32_e32 v177, v176
	s_waitcnt vmcnt(4)
	v_mov_b32_e32 v174, v126
	v_mov_b32_e32 v175, v30
	v_mov_b32_e32 v30, v127
	v_add_u32_e32 v126, -1, v177
	v_fma_f32 v127, -v126, v177, v176
	v_cmp_ge_f32_e64 s[6:7], 0, v127
	v_add_u32_e32 v127, 1, v177
	s_mov_b32 s49, s48
	v_cndmask_b32_e64 v126, v177, v126, s[6:7]
	v_fma_f32 v177, -v127, v177, v176
	v_cmp_lt_f32_e64 s[6:7], 0, v177
	s_nop 1
	v_cndmask_b32_e64 v126, v126, v127, s[6:7]
	v_mul_f32_e32 v127, 0x37800000, v126
	v_cndmask_b32_e32 v126, v126, v127, vcc
	v_cmp_class_f32_e32 vcc, v176, v254
	v_mov_b32_e32 v127, v28
	v_mov_b32_e32 v28, v125
	v_cndmask_b32_e32 v176, v126, v176, vcc
	v_div_scale_f32 v177, s[6:7], v176, v176, 1.0
	v_rcp_f32_e32 v192, v177
	v_mov_b32_e32 v126, v124
	v_mov_b32_e32 v124, v0
	v_mov_b32_e32 v125, v4
	v_fma_f32 v193, -v177, v192, 1.0
	v_fmac_f32_e32 v192, v193, v192
	v_div_scale_f32 v193, vcc, 1.0, v176, 1.0
	v_mul_f32_e32 v194, v193, v192
	v_fma_f32 v195, -v177, v194, v193
	v_fmac_f32_e32 v194, v195, v192
	v_fma_f32 v177, -v177, v194, v193
	v_div_fmas_f32 v177, v177, v192, v194
	v_div_fixup_f32 v176, v177, v176, 1.0
	v_mul_f32_e32 v176, 0x3dd53b94, v176
	v_mul_f32_e32 v109, v109, v176
	v_mul_f32_e32 v230, v109, v230
	v_mov_b32_e32 v109, v38
	v_mov_b32_e32 v38, v47
	v_mov_b32_e32 v47, v36
	v_mul_f32_e32 v36, v88, v176
	v_mul_f32_e32 v218, v36, v218
	v_mul_f32_e32 v36, v89, v176
	v_mul_f32_e32 v217, v36, v217
	v_mul_f32_e32 v36, v90, v176
	v_mul_f32_e32 v90, v36, v216
	v_mul_f32_e32 v36, v91, v176
	v_mul_f32_e32 v91, v36, v215
	v_mul_f32_e32 v36, v84, v176
	v_mul_f32_e32 v84, v36, v214
	v_mul_f32_e32 v36, v85, v176
	v_mul_f32_e32 v85, v36, v213
	v_mul_f32_e32 v36, v86, v176
	v_mul_f32_e32 v86, v36, v212
	v_mul_f32_e32 v36, v87, v176
	v_mul_f32_e32 v87, v36, v211
	v_mul_f32_e32 v36, v176, v80
	v_mul_f32_e32 v80, v36, v210
	v_mul_f32_e32 v36, v176, v81
	v_mul_f32_e32 v81, v36, v209
	v_mul_f32_e32 v36, v176, v82
	v_mul_f32_e32 v82, v36, v208
	v_mul_f32_e32 v36, v176, v83
	v_mul_f32_e32 v83, v36, v207
	v_mul_f32_e32 v36, v176, v76
	v_mul_f32_e32 v76, v36, v206
	v_mul_f32_e32 v36, v176, v77
	v_mul_f32_e32 v77, v36, v205
	v_mul_f32_e32 v36, v176, v78
	v_mul_f32_e32 v78, v36, v204
	v_mul_f32_e32 v36, v176, v79
	v_mul_f32_e32 v79, v36, v203
	v_mul_f32_e32 v36, v176, v72
	v_mul_f32_e32 v72, v36, v202
	v_mul_f32_e32 v36, v176, v73
	v_mul_f32_e32 v73, v36, v201
	v_mul_f32_e32 v36, v176, v74
	v_mul_f32_e32 v74, v36, v200
	v_mul_f32_e32 v36, v176, v75
	v_mul_f32_e32 v75, v36, v199
	v_mul_f32_e32 v36, v176, v68
	v_mul_f32_e32 v68, v36, v198
	v_mul_f32_e32 v36, v176, v69
	v_mul_f32_e32 v69, v36, v197
	v_mul_f32_e32 v36, v176, v70
	v_mul_f32_e32 v70, v36, v196
	v_mul_f32_e32 v36, v176, v71
	v_mul_f32_e32 v71, v36, v187
	v_mul_f32_e32 v36, v176, v64
	v_mul_f32_e32 v64, v36, v186
	v_mul_f32_e32 v36, v176, v65
	v_mul_f32_e32 v65, v36, v183
	v_mul_f32_e32 v36, v176, v66
	v_mul_f32_e32 v66, v36, v182
	v_mul_f32_e32 v36, v176, v67
	v_mul_f32_e32 v67, v36, v181
	v_mul_f32_e32 v36, v176, v56
	v_mul_f32_e32 v56, v36, v180
	v_mul_f32_e32 v36, v176, v57
	v_mul_f32_e32 v57, v36, v179
	v_mul_f32_e32 v36, v176, v58
	v_mul_f32_e32 v32, v176, v32
	v_mul_f32_e32 v58, v36, v171
	v_mul_f32_e32 v171, v32, v237
	v_mul_f32_e32 v32, v176, v33
	v_mul_f32_e32 v179, v32, v235
	v_mul_f32_e32 v32, v176, v34
	v_mul_f32_e32 v36, v176, v59
	v_mul_f32_e32 v180, v32, v233
	v_mul_f32_e32 v32, v176, v35
	v_mul_f32_e32 v59, v36, v170
	v_mul_f32_e32 v36, v176, v48
	v_mul_f32_e32 v181, v32, v231
	v_mul_f32_e32 v32, v176, v60
	v_mul_f32_e32 v169, v36, v169
	v_mul_f32_e32 v36, v176, v49
	v_mul_f32_e32 v60, v32, v241
	v_mul_f32_e32 v32, v176, v61
	v_mul_f32_e32 v168, v36, v168
	v_mul_f32_e32 v36, v176, v50
	v_mul_f32_e32 v61, v32, v244
	v_mul_f32_e32 v32, v176, v62
	v_mul_f32_e32 v167, v36, v167
	v_mul_f32_e32 v36, v176, v51
	v_mul_f32_e32 v62, v32, v245
	v_mul_f32_e32 v32, v176, v63
	v_mul_f32_e32 v166, v36, v166
	v_mul_f32_e32 v36, v176, v40
	v_mul_f32_e32 v63, v32, v240
	v_mul_f32_e32 v32, v176, v52
	v_mul_f32_e32 v165, v36, v165
	v_mul_f32_e32 v36, v176, v41
	v_mul_f32_e32 v182, v32, v238
	v_mul_f32_e32 v32, v176, v53
	v_mul_f32_e32 v108, v108, v176
	v_mul_f32_e32 v177, v104, v176
	v_mul_f32_e32 v164, v36, v164
	v_mul_f32_e32 v36, v176, v42
	v_mul_f32_e32 v183, v32, v236
	v_mul_f32_e32 v32, v176, v54
	v_mul_f32_e32 v229, v108, v229
	v_mul_f32_e32 v177, v177, v225
	v_mov_b32_e32 v108, v46
	v_mov_b32_e32 v46, v44
	v_mul_f32_e32 v163, v36, v163
	v_mul_f32_e32 v36, v176, v43
	v_mul_f32_e32 v54, v32, v234
	v_mul_f32_e32 v32, v176, v55
	v_mul_f32_e32 v170, v36, v239
	v_mul_f32_e32 v55, v32, v232
	v_pk_mul_f32 v[32:33], v[176:177], v[46:47] op_sel_hi:[0,1]
	v_mov_b32_e32 v36, v45
	s_waitcnt vmcnt(1)
	v_mov_b32_e32 v88, v100
	s_waitcnt vmcnt(0)
; __device__ __forceinline__ u32x4 pack8(const float* f) { u32x4 w; w.x = cvt_pk_bf16(f[0], f[1]); w.y = cvt_pk_bf16(f[2], f[3]); w.z = cvt_pk_bf16(f[4], f[5]); w.w = cvt_pk_bf16(f[6], f[7]); return w; }
; __device__ __forceinline__ void attn_unit(const bf16_t* __restrict__ Qb, const bf16_t* __restrict__ KV, const bf16_t* __restrict__ KP, bf16_t* __restrict__ Ob, ...
;     ...
;     if (do_rope) { const int s = (qrow0 + wid * QBLK + r32) & (SEQ - 1), pr_ = s >> 6, pc_ = s & 63;
; #pragma unroll
;       for (int ax = 0; ax < 2; ++ax) { const float* cp = rope + (ax ? pc_ : pr_) * 16 + hi * 8; const f32x4 c0 = *(const f32x4*)cp, c1 = *(const f32x4*)(cp + 4), s0 = *(const f32x4*)(cp + 1024), s1 = *(const f32x4*)(cp + 1028);
; #pragma unroll
;         for (int jj = 0; jj < 8; ++jj) { const float c = jj < 4 ? c0[jj & 3] : c1[jj & 3], sn = jj < 4 ? s0[jj & 3] : s1[jj & 3], a = qf[8 + 2 * ax][jj], b = qf[9 + 2 * ax][jj];
;           qf[8 + 2 * ax][jj] = a * c - b * sn; qf[9 + 2 * ax][jj] = b * c + a * sn; } } }
; #pragma unroll
;     for (int d0 = 0; d0 < 12; ++d0) { const u32x4 w = pack8(qf[d0]); qr[d0] = *reinterpret_cast<const bf16x8*>(&w); }
	v_mov_b32_e32 v89, v112
	v_pk_mul_f32 v[32:33], v[32:33], v[158:159]
	v_pk_mul_f32 v[34:35], v[176:177], v[36:37] op_sel_hi:[0,1]
	v_mov_b32_e32 v52, v112
	v_mov_b32_e32 v53, v100
	v_pk_mul_f32 v[34:35], v[34:35], v[160:161]
	v_pk_mul_f32 v[52:53], v[32:33], v[52:53]
	v_pk_mul_f32 v[32:33], v[32:33], v[88:89]
	v_mov_b32_e32 v100, v113
	v_sub_f32_e32 v52, v53, v52
	v_add_f32_e32 v53, v32, v33
	v_pk_mul_f32 v[32:33], v[34:35], v[100:101]
	v_mov_b32_e32 v112, v101
	v_pk_mul_f32 v[36:37], v[176:177], v[108:109] op_sel_hi:[0,1]
	v_sub_f32_e32 v88, v33, v32
	v_pk_mul_f32 v[32:33], v[34:35], v[112:113]
	v_mul_f32_e32 v110, v110, v176
	v_mul_f32_e32 v111, v111, v176
	v_pk_mul_f32 v[36:37], v[36:37], v[154:155]
	v_add_f32_e32 v34, v32, v33
	v_mov_b32_e32 v32, v114
	v_mov_b32_e32 v33, v102
	v_mul_f32_e32 v227, v110, v227
	v_mul_f32_e32 v228, v111, v228
	v_mov_b32_e32 v110, v102
	v_mov_b32_e32 v111, v114
	v_pk_mul_f32 v[38:39], v[176:177], v[38:39] op_sel_hi:[0,1]
	v_pk_mul_f32 v[32:33], v[36:37], v[32:33]
	v_pk_mul_f32 v[38:39], v[38:39], v[156:157]
	v_sub_f32_e32 v35, v33, v32
	v_pk_mul_f32 v[32:33], v[36:37], v[110:111]
	v_mov_b32_e32 v102, v115
	v_add_f32_e32 v36, v32, v33
	v_pk_mul_f32 v[32:33], v[38:39], v[102:103]
	v_mov_b32_e32 v114, v103
	v_pk_mul_f32 v[40:41], v[176:177], v[126:127] op_sel_hi:[0,1]
	v_sub_f32_e32 v37, v33, v32
	v_pk_mul_f32 v[32:33], v[38:39], v[114:115]
	v_pk_mul_f32 v[40:41], v[40:41], v[150:151]
	v_add_f32_e32 v38, v32, v33
	v_mov_b32_e32 v32, v96
	v_mov_b32_e32 v33, v24
	v_mul_f32_e32 v193, v106, v176
	v_mul_f32_e32 v194, v107, v176
	v_mov_b32_e32 v106, v24
	v_mov_b32_e32 v107, v96
	v_pk_mul_f32 v[28:29], v[176:177], v[28:29] op_sel_hi:[0,1]
	v_pk_mul_f32 v[32:33], v[40:41], v[32:33]
	v_pk_mul_f32 v[28:29], v[28:29], v[152:153]
	v_sub_f32_e32 v39, v33, v32
	v_pk_mul_f32 v[32:33], v[40:41], v[106:107]
	v_mov_b32_e32 v24, v97
	v_mov_b32_e32 v96, v25
	v_pk_mul_f32 v[42:43], v[176:177], v[174:175] op_sel_hi:[0,1]
	v_add_f32_e32 v40, v32, v33
	v_pk_mul_f32 v[32:33], v[28:29], v[24:25]
	v_pk_mul_f32 v[24:25], v[28:29], v[96:97]
	v_pk_mul_f32 v[42:43], v[42:43], v[146:147]
	v_add_f32_e32 v28, v24, v25
	v_mov_b32_e32 v24, v98
	v_mov_b32_e32 v25, v26
	v_mul_f32_e32 v192, v105, v176
	v_mov_b32_e32 v104, v26
	v_mov_b32_e32 v105, v98
	v_pk_mul_f32 v[30:31], v[176:177], v[30:31] op_sel_hi:[0,1]
	v_pk_mul_f32 v[24:25], v[42:43], v[24:25]
	v_pk_mul_f32 v[30:31], v[30:31], v[148:149]
	v_sub_f32_e32 v29, v25, v24
	v_pk_mul_f32 v[24:25], v[42:43], v[104:105]
	v_mov_b32_e32 v26, v99
	v_sub_f32_e32 v32, v33, v32
	v_add_f32_e32 v33, v24, v25
	v_pk_mul_f32 v[24:25], v[30:31], v[26:27]
	v_mov_b32_e32 v98, v27
	v_pk_mul_f32 v[44:45], v[176:177], v[144:145] op_sel_hi:[0,1]
	v_sub_f32_e32 v26, v25, v24
	v_pk_mul_f32 v[24:25], v[30:31], v[98:99]
	v_pk_mul_f32 v[44:45], v[44:45], v[142:143]
	v_add_f32_e32 v27, v24, v25
	v_mov_b32_e32 v24, v12
	v_mov_b32_e32 v25, v8
	v_mul_f32_e32 v243, v94, v176
	v_mul_f32_e32 v246, v95, v176
	v_mov_b32_e32 v94, v8
	v_mov_b32_e32 v95, v12
	v_pk_mul_f32 v[20:21], v[176:177], v[20:21] op_sel_hi:[0,1]
	v_pk_mul_f32 v[24:25], v[44:45], v[24:25]
	v_pk_mul_f32 v[20:21], v[20:21], v[116:117]
	v_sub_f32_e32 v30, v25, v24
	v_pk_mul_f32 v[24:25], v[44:45], v[94:95]
	v_mov_b32_e32 v8, v13
	v_mov_b32_e32 v12, v9
	v_pk_mul_f32 v[46:47], v[176:177], v[138:139] op_sel_hi:[0,1]
	v_add_f32_e32 v31, v24, v25
	v_pk_mul_f32 v[24:25], v[20:21], v[8:9]
	v_pk_mul_f32 v[8:9], v[20:21], v[12:13]
	v_pk_mul_f32 v[46:47], v[46:47], v[122:123]
	v_add_f32_e32 v12, v8, v9
	v_mov_b32_e32 v8, v14
	v_mov_b32_e32 v9, v10
	v_mul_f32_e32 v195, v92, v176
	v_mul_f32_e32 v242, v93, v176
	v_mov_b32_e32 v92, v10
	v_mov_b32_e32 v93, v14
	v_pk_mul_f32 v[22:23], v[176:177], v[22:23] op_sel_hi:[0,1]
	v_pk_mul_f32 v[8:9], v[46:47], v[8:9]
	v_pk_mul_f32 v[22:23], v[22:23], v[140:141]
	v_sub_f32_e32 v13, v9, v8
	v_pk_mul_f32 v[8:9], v[46:47], v[92:93]
	v_mov_b32_e32 v10, v15
	v_add_f32_e32 v20, v8, v9
	v_pk_mul_f32 v[8:9], v[22:23], v[10:11]
	v_mov_b32_e32 v14, v11
	v_pk_mul_f32 v[48:49], v[176:177], v[136:137] op_sel_hi:[0,1]
	v_sub_f32_e32 v10, v9, v8
	v_pk_mul_f32 v[8:9], v[22:23], v[14:15]
	v_pk_mul_f32 v[48:49], v[48:49], v[134:135]
	v_add_f32_e32 v11, v8, v9
	v_mov_b32_e32 v8, v4
	v_mov_b32_e32 v9, v0
	v_pk_mul_f32 v[16:17], v[176:177], v[16:17] op_sel_hi:[0,1]
	v_pk_mul_f32 v[8:9], v[48:49], v[8:9]
	v_pk_mul_f32 v[16:17], v[16:17], v[118:119]
	v_sub_f32_e32 v14, v9, v8
	v_pk_mul_f32 v[8:9], v[48:49], v[124:125]
	v_mov_b32_e32 v0, v5
	v_mov_b32_e32 v4, v1
	v_pk_mul_f32 v[50:51], v[176:177], v[130:131] op_sel_hi:[0,1]
	v_add_f32_e32 v15, v8, v9
	v_pk_mul_f32 v[8:9], v[16:17], v[0:1]
	v_pk_mul_f32 v[0:1], v[16:17], v[4:5]
	v_pk_mul_f32 v[50:51], v[50:51], v[128:129]
	v_add_f32_e32 v4, v0, v1
	v_mov_b32_e32 v0, v6
	v_mov_b32_e32 v1, v2
	v_pk_mul_f32 v[18:19], v[176:177], v[18:19] op_sel_hi:[0,1]
	v_pk_mul_f32 v[0:1], v[50:51], v[0:1]
	v_pk_mul_f32 v[18:19], v[18:19], v[132:133]
	v_sub_f32_e32 v5, v1, v0
	v_pk_mul_f32 v[0:1], v[50:51], v[120:121]
	v_mov_b32_e32 v2, v7
	v_sub_f32_e32 v8, v9, v8
	v_add_f32_e32 v9, v0, v1
	v_pk_mul_f32 v[0:1], v[18:19], v[2:3]
	v_mov_b32_e32 v6, v3
	v_sub_f32_e32 v2, v1, v0
	v_pk_mul_f32 v[0:1], v[18:19], v[6:7]
	v_mul_f32_e32 v192, v192, v226
	v_mul_f32_e32 v193, v193, v223
	v_mul_f32_e32 v194, v194, v224
	v_mul_f32_e32 v195, v195, v221
	v_mul_f32_e32 v221, v242, v222
	v_mul_f32_e32 v219, v243, v219
	v_mul_f32_e32 v220, v246, v220
	v_add_f32_e32 v0, v0, v1
	v_cvt_pk_bf16_f32 v136, v229, v230
	v_cvt_pk_bf16_f32 v137, v227, v228
	v_cvt_pk_bf16_f32 v138, v177, v192
	v_cvt_pk_bf16_f32 v139, v193, v194
	v_cvt_pk_bf16_f32 v132, v195, v221
; __device__ __forceinline__ u32x4 pack8(const float* f) { u32x4 w; w.x = cvt_pk_bf16(f[0], f[1]); w.y = cvt_pk_bf16(f[2], f[3]); w.z = cvt_pk_bf16(f[4], f[5]); w.w = cvt_pk_bf16(f[6], f[7]); return w; }
; __device__ __forceinline__ int v_st(int k, int c) { const int kk = (k & ~0xC) | ((k & 4) << 1) | ((k & 8) >> 1); return ((kk >> 3) * 4 + (c >> 5)) * 512 + ((kk & 7) * 32 + (c & 31)) * 2; }
; __device__ __forceinline__ int v_rd_base(int lane) { return ((lane & 3) << 3) | (((lane >> 2) & 3) << 6) | (((lane >> 4) & 1) << 5) | (((lane >> 5) & 1) << 8); }
; #define SLOAD(j) do { const int r0_ = TROW(j); const bf16_t* a_ = KVh + (size_t)(r0_ + sr) * LDKV + sc; const bf16_t* b_ = KVh + (size_t)(r0_ + 32 + sr) * LDKV + sc; \
;     vs0 = ld8(a_ + 128); vs1 = ld8(b_ + 128); ks0 = ld8(a_); ks1 = ld8(b_); kp0 = ld8(KPh + (size_t)(r0_ + pr) * LDKP + pc); } while (0)
; #define SWRITE(b) do { *(bf16x8*)(V_lds + (b) * SHM_V + vst0) = vs0; *(bf16x8*)(V_lds + (b) * SHM_V + vst1) = vs1; const int kc = sc * 2; \
;     *(bf16x8*)(KN_lds + (b) * SHM_KN + KSWZ(sr, kc)) = ks0; *(bf16x8*)(KN_lds + (b) * SHM_KN + KSWZ(32 + sr, kc)) = ks1; \
;     *(bf16x8*)(KP_lds + (b) * SHM_KP + KPSWZ(pr, pc * 2)) = kp0; } while (0)
; #define SWAIT() asm volatile("s_waitcnt vmcnt(0)" ::: "memory")
; __device__ __forceinline__ void attn_unit(const bf16_t* __restrict__ Qb, const bf16_t* __restrict__ KV, const bf16_t* __restrict__ KP, bf16_t* __restrict__ Ob, ...
;     ...
;     for (int d0 = 0; d0 < 12; ++d0) { const u32x4 w = pack8(qf[d0]); qr[d0] = *reinterpret_cast<const bf16x8*>(&w); }
;   }
;   const int sr = tid >> 4, sc = (tid & 15) * 8, vst0 = v_st(sr, sc), vst1 = v_st(32 + sr, sc);
;   const int pr = tid >> 3, pc = (tid & 7) * 8;
;   const int vb0 = (int)(uintptr_t)V_lds + v_rd_base(lane);
;   bf16x8 vs0, vs1, ks0, ks1, kp0;
;   const bf16_t* KVh = KV + h * 256; const bf16_t* KPh = KP + h * QKR;
;     ...
;   f32x16 pA0, pA1, pB0, pB1; float mnA, mnB, alA, alB; bf16x8 pa0, pa1, pa2, pa3;
;   SLOAD(0); SWAIT(); SWRITE(0); __syncthreads();
	v_cvt_pk_bf16_f32 v133, v219, v220
	v_cvt_pk_bf16_f32 v134, v218, v217
	v_cvt_pk_bf16_f32 v135, v90, v91
	v_cvt_pk_bf16_f32 v128, v84, v85
	v_cvt_pk_bf16_f32 v129, v86, v87
	v_cvt_pk_bf16_f32 v130, v80, v81
	v_cvt_pk_bf16_f32 v131, v82, v83
	v_cvt_pk_bf16_f32 v124, v76, v77
	v_cvt_pk_bf16_f32 v125, v78, v79
	v_cvt_pk_bf16_f32 v126, v72, v73
	v_cvt_pk_bf16_f32 v127, v74, v75
	v_cvt_pk_bf16_f32 v120, v68, v69
	v_cvt_pk_bf16_f32 v121, v70, v71
	v_cvt_pk_bf16_f32 v122, v64, v65
	v_cvt_pk_bf16_f32 v123, v66, v67
	v_cvt_pk_bf16_f32 v140, v56, v57
	v_cvt_pk_bf16_f32 v141, v58, v59
	v_cvt_pk_bf16_f32 v142, v169, v168
	v_cvt_pk_bf16_f32 v143, v167, v166
	v_cvt_pk_bf16_f32 v116, v165, v164
	v_cvt_pk_bf16_f32 v117, v163, v170
	v_cvt_pk_bf16_f32 v118, v171, v179
	v_cvt_pk_bf16_f32 v119, v180, v181
	v_cvt_pk_bf16_f32 v112, v60, v61
	v_cvt_pk_bf16_f32 v113, v62, v63
	v_cvt_pk_bf16_f32 v114, v182, v183
	v_cvt_pk_bf16_f32 v115, v54, v55
	v_cvt_pk_bf16_f32 v108, v52, v88
	v_lshlrev_b32_e32 v52, 3, v162
	v_sub_f32_e32 v24, v25, v24
	v_cvt_pk_bf16_f32 v109, v35, v37
	v_cvt_pk_bf16_f32 v110, v39, v32
	v_cvt_pk_bf16_f32 v111, v29, v26
	v_cvt_pk_bf16_f32 v104, v53, v34
	v_cvt_pk_bf16_f32 v105, v36, v38
	v_cvt_pk_bf16_f32 v106, v40, v28
	v_cvt_pk_bf16_f32 v107, v33, v27
	v_cvt_pk_bf16_f32 v100, v30, v24
	v_cvt_pk_bf16_f32 v101, v13, v10
	v_cvt_pk_bf16_f32 v102, v14, v8
	v_cvt_pk_bf16_f32 v103, v5, v2
	v_cvt_pk_bf16_f32 v96, v31, v12
	v_cvt_pk_bf16_f32 v97, v20, v11
	v_cvt_pk_bf16_f32 v98, v15, v4
	v_cvt_pk_bf16_f32 v99, v9, v0
	v_ashrrev_i32_e32 v198, 4, v162
	v_and_b32_e32 v0, 0x78, v52
	v_lshlrev_b32_e32 v48, 1, v0
	s_lshl_b32 s6, s3, 9
	v_add_u32_e32 v0, s31, v198
	s_add_u32 s6, s27, s6
	v_ashrrev_i32_e32 v1, 31, v0
	s_addc_u32 s7, s28, 0
	v_lshlrev_b64 v[0:1], 12, v[0:1]
	v_lshl_add_u64 v[0:1], s[6:7], 0, v[0:1]
	v_mov_b32_e32 v49, v173
	v_add_u32_e32 v53, s25, v198
	v_lshl_add_u64 v[8:9], v[0:1], 0, v[48:49]
	v_add_u32_e32 v0, 0x4020, v53
	v_ashrrev_i32_e32 v1, 31, v0
	v_lshlrev_b64 v[0:1], 12, v[0:1]
	v_lshl_add_u64 v[4:5], s[6:7], 0, v[0:1]
	global_load_dwordx4 v[0:3], v[8:9], off offset:256
	v_ashrrev_i32_e32 v199, 3, v162
	s_lshl_b32 s8, s3, 7
	v_add_u32_e32 v16, s31, v199
	s_add_u32 s8, s29, s8
	v_ashrrev_i32_e32 v17, 31, v16
	v_lshlrev_b32_e32 v72, 4, v162
	s_addc_u32 s9, s30, 0
	v_lshlrev_b64 v[16:17], 10, v[16:17]
	v_lshl_add_u64 v[12:13], v[4:5], 0, v[48:49]
	v_lshl_add_u64 v[16:17], s[8:9], 0, v[16:17]
	v_and_b32_e32 v50, 0x70, v72
	v_mov_b32_e32 v51, v173
	global_load_dwordx4 v[4:7], v[12:13], off offset:256
	v_lshl_add_u64 v[16:17], v[16:17], 0, v[50:51]
	global_load_dwordx4 v[8:11], v[8:9], off
	v_and_b32_e32 v20, 0xfffff0, v198
	global_load_dwordx4 v[12:15], v[12:13], off
	v_lshlrev_b32_e32 v21, 1, v198
	global_load_dwordx4 v[16:19], v[16:17], off
	v_and_or_b32 v20, v21, 8, v20
	v_lshrrev_b32_e32 v21, 1, v198
	v_lshrrev_b32_e32 v20, 1, v20
	v_bfe_u32 v22, v52, 5, 2
	v_and_b32_e32 v23, 3, v198
	v_or_b32_e32 v20, v20, v22
	v_and_or_b32 v21, v21, 4, v23
	v_lshlrev_b32_e32 v20, 9, v20
	v_lshlrev_b32_e32 v21, 6, v21
	v_and_b32_e32 v23, 48, v48
	v_or3_b32 v20, v20, v21, v23
	v_add_u32_e32 v200, 32, v198
	v_and_b32_e32 v24, 0xfffff0, v200
	v_lshlrev_b32_e32 v25, 1, v200
	v_add_u32_e32 v201, 0, v20
	v_and_or_b32 v24, v25, 8, v24
	s_waitcnt vmcnt(0)
	v_lshrrev_b32_e32 v24, 1, v24
	v_or_b32_e32 v22, v24, v22
	v_lshlrev_b32_e32 v22, 9, v22
	v_or3_b32 v21, v22, v21, v23
	v_add_u32_e32 v202, 0, v21
	s_add_i32 s31, 0, 0x10000
	v_and_b32_e32 v74, 63, v162
	v_mov_b32_e32 v77, 0xf149f2ca
	v_lshl_add_u64 v[180:181], s[6:7], 0, v[48:49]
	v_lshl_add_u64 v[182:183], s[8:9], 0, v[50:51]
	v_mov_b32_e32 v187, 0
	s_waitcnt vmcnt(4)
	ds_write_b128 v201, v[0:3]
	v_lshlrev_b32_e32 v0, 8, v198
	v_and_b32_e32 v1, 0xf0, v162
	v_bitop3_b32 v0, v48, v0, v1 bitop3:0xde
	v_add_u32_e32 v203, 0, v0
	v_lshlrev_b32_e32 v0, 8, v200
	v_bitop3_b32 v0, v48, v0, v1 bitop3:0xde
	v_add_u32_e32 v204, 0, v0
	v_lshlrev_b32_e32 v0, 7, v199
	v_and_b32_e32 v1, 0x70, v162
	v_bitop3_b32 v73, v50, v0, v1 bitop3:0xde
	v_add_u32_e32 v0, s31, v73
	v_add_u32_e32 v222, 0, v73
	s_waitcnt vmcnt(3)
	ds_write_b128 v202, v[4:7]
	v_add_u32_e32 v223, 0x12000, v222
	s_waitcnt vmcnt(2)
	ds_write_b128 v203, v[8:11] offset:32768
	v_lshlrev_b32_e32 v8, 8, v184
	v_and_b32_e32 v9, 0xf0, v72
	s_waitcnt vmcnt(1)
	ds_write_b128 v204, v[12:15] offset:32768
	s_waitcnt vmcnt(0)
	ds_write_b128 v0, v[16:19]
	v_bitop3_b32 v0, v172, v8, v9 bitop3:0xde
	v_add_u32_e32 v205, 0, v0
	s_waitcnt lgkmcnt(0)
	s_barrier
; __device__ __forceinline__ int v_st(int k, int c) { const int kk = (k & ~0xC) | ((k & 4) << 1) | ((k & 8) >> 1); return ((kk >> 3) * 4 + (c >> 5)) * 512 + ((kk & 7) * 32 + (c & 31)) * 2; }
; __device__ __forceinline__ int v_rd_base(int lane) { return ((lane & 3) << 3) | (((lane >> 2) & 3) << 6) | (((lane >> 4) & 1) << 5) | (((lane >> 5) & 1) << 8); }
; #define SLOAD(j) do { const int r0_ = TROW(j); const bf16_t* a_ = KVh + (size_t)(r0_ + sr) * LDKV + sc; const bf16_t* b_ = KVh + (size_t)(r0_ + 32 + sr) * LDKV + sc; \
;     vs0 = ld8(a_ + 128); vs1 = ld8(b_ + 128); ks0 = ld8(a_); ks1 = ld8(b_); kp0 = ld8(KPh + (size_t)(r0_ + pr) * LDKP + pc); } while (0)
; #define SWRITE(b) do { *(bf16x8*)(V_lds + (b) * SHM_V + vst0) = vs0; *(bf16x8*)(V_lds + (b) * SHM_V + vst1) = vs1; const int kc = sc * 2; \
;     *(bf16x8*)(KN_lds + (b) * SHM_KN + KSWZ(sr, kc)) = ks0; *(bf16x8*)(KN_lds + (b) * SHM_KN + KSWZ(32 + sr, kc)) = ks1; \
;     *(bf16x8*)(KP_lds + (b) * SHM_KP + KPSWZ(pr, pc * 2)) = kp0; } while (0)
; #define SWAIT() asm volatile("s_waitcnt vmcnt(0)" ::: "memory")
; __device__ __forceinline__ void attn_unit(const bf16_t* __restrict__ Qb, const bf16_t* __restrict__ KV, const bf16_t* __restrict__ KP, bf16_t* __restrict__ Ob, ...
;     ...
;   const int sr = tid >> 4, sc = (tid & 15) * 8, vst0 = v_st(sr, sc), vst1 = v_st(32 + sr, sc);
;   const int pr = tid >> 3, pc = (tid & 7) * 8;
;   const int vb0 = (int)(uintptr_t)V_lds + v_rd_base(lane);
;   bf16x8 vs0, vs1, ks0, ks1, kp0;
;   const bf16_t* KVh = KV + h * 256; const bf16_t* KPh = KP + h * QKR;
;     ...
;   f32x16 pA0, pA1, pB0, pB1; float mnA, mnB, alA, alB; bf16x8 pa0, pa1, pa2, pa3;
;   SLOAD(0); SWAIT(); SWRITE(0); __syncthreads();
;   qkt(pA0, pA1, KN_lds, KP_lds, qr, r32, hi); partialSM(pA0, pA1, m_reg, mnA, alA);
;   SLOAD(1);
;   SWAIT(); SWRITE(1); __syncthreads();
;   for (int j = 1; j + 1 < NT; j += 2) {
	s_movk_i32 s49, 0x1000
	s_waitcnt vmcnt(0)
	v_readfirstlane_b32 s40, v188
	s_nop 1
	s_lshr_b32 s40, s40, 6
	s_lshr_b32 s41, s40, 2
	v_and_b32_e32 v187, 0x3fffffc0, v188
	v_lshlrev_b32_e32 v179, 2, v187
	v_add_u32_e32 v179, 0x14000, v179
	v_lshl_add_u32 v186, v184, 2, v179
	v_and_b32_e32 v187, 63, v188
	v_cmp_gt_u32_e64 s[6:7], 32, v187
	s_add_i32 s31, s25, 0x4000
	s_lshl_b32 s44, s3, 9
	s_add_u32 s47, s27, s44
	s_addc_u32 s63, s28, 0
	s_lshl_b32 s44, s3, 7
	s_add_u32 s60, s29, s44
	s_addc_u32 s61, s30, 0
	v_lshrrev_b32_e32 v180, 4, v188
	v_lshlrev_b32_e32 v180, 12, v180
	v_and_b32_e32 v181, 15, v188
	v_lshl_or_b32 v180, v181, 4, v180
	v_lshrrev_b32_e32 v181, 3, v188
	v_lshlrev_b32_e32 v181, 10, v181
	v_and_b32_e32 v182, 7, v188
	v_lshl_or_b32 v181, v182, 4, v181
	v_lshlrev_b32_e32 v250, 8, v184
	v_and_b32_e32 v251, 15, v184
	v_lshlrev_b32_e32 v251, 4, v251
	v_or_b32_e32 v249, 0, v172
	v_xor_b32_e32 v249, v249, v251
	v_or_b32_e32 v249, v249, v250
	v_add_u32_e32 v160, 0x8000, v249
	v_or_b32_e32 v249, 32, v172
	v_xor_b32_e32 v249, v249, v251
	v_or_b32_e32 v249, v249, v250
	v_add_u32_e32 v161, 0x8000, v249
	v_or_b32_e32 v249, 64, v172
	v_xor_b32_e32 v249, v249, v251
	v_or_b32_e32 v249, v249, v250
	v_add_u32_e32 v162, 0x8000, v249
	v_or_b32_e32 v249, 96, v172
	v_xor_b32_e32 v249, v249, v251
	v_or_b32_e32 v249, v249, v250
	v_add_u32_e32 v163, 0x8000, v249
	v_or_b32_e32 v249, 128, v172
	v_xor_b32_e32 v249, v249, v251
	v_or_b32_e32 v249, v249, v250
	v_add_u32_e32 v164, 0x8000, v249
	v_or_b32_e32 v249, 160, v172
	v_xor_b32_e32 v249, v249, v251
	v_or_b32_e32 v249, v249, v250
	v_add_u32_e32 v165, 0x8000, v249
	v_or_b32_e32 v249, 192, v172
	v_xor_b32_e32 v249, v249, v251
	v_or_b32_e32 v249, v249, v250
	v_add_u32_e32 v166, 0x8000, v249
	v_or_b32_e32 v249, 224, v172
	v_xor_b32_e32 v249, v249, v251
	v_or_b32_e32 v249, v249, v250
	v_add_u32_e32 v167, 0x8000, v249
	v_lshlrev_b32_e32 v250, 7, v184
	v_lshrrev_b32_e32 v251, 1, v184
	v_and_b32_e32 v251, 7, v251
	v_lshlrev_b32_e32 v251, 4, v251
	v_or_b32_e32 v249, 0, v172
	v_xor_b32_e32 v249, v249, v251
	v_or_b32_e32 v249, v249, v250
	v_add_u32_e32 v168, 0x10000, v249
	v_or_b32_e32 v249, 32, v172
	v_xor_b32_e32 v249, v249, v251
	v_or_b32_e32 v249, v249, v250
	v_add_u32_e32 v169, 0x10000, v249
	v_or_b32_e32 v249, 64, v172
	v_xor_b32_e32 v249, v249, v251
	v_or_b32_e32 v249, v249, v250
	v_add_u32_e32 v170, 0x10000, v249
	v_or_b32_e32 v249, 96, v172
	v_xor_b32_e32 v249, v249, v251
	v_or_b32_e32 v249, v249, v250
	v_add_u32_e32 v171, 0x10000, v249
	v_and_b32_e32 v187, 63, v188
	v_lshlrev_b32_e32 v249, 3, v187
	v_lshlrev_b32_e32 v250, 4, v187
	v_and_b32_e32 v250, 0xc0, v250
	v_and_or_b32 v250, v249, 24, v250
	v_lshlrev_b32_e32 v251, 1, v187
	v_and_b32_e32 v251, 32, v251
	v_and_b32_e32 v249, 0x100, v249
	v_or3_b32 v174, v250, v251, v249
	v_mov_b32_e32 v244, v201
	v_mov_b32_e32 v245, v202
	v_add_u32_e32 v246, 0xc000, v203
	v_add_u32_e32 v247, 0xc000, v204
	v_add_u32_e32 v248, 0x12000, v222
	v_mov_b32_e32 v175, 0
	s_mov_b32 s62, 0
	s_mov_b32 s64, 0x42800000
	v_mov_b32_e32 v176, 0
	v_mov_b32_e32 v0, 0
	v_mov_b32_e32 v1, 0
	v_mov_b32_e32 v2, 0
	v_mov_b32_e32 v3, 0
	v_mov_b32_e32 v4, 0
	v_mov_b32_e32 v5, 0
	v_mov_b32_e32 v6, 0
	v_mov_b32_e32 v7, 0
	v_mov_b32_e32 v8, 0
	v_mov_b32_e32 v9, 0
	v_mov_b32_e32 v10, 0
	v_mov_b32_e32 v11, 0
	v_mov_b32_e32 v12, 0
	v_mov_b32_e32 v13, 0
	v_mov_b32_e32 v14, 0
	v_mov_b32_e32 v15, 0
	v_mov_b32_e32 v16, 0
	v_mov_b32_e32 v17, 0
	v_mov_b32_e32 v18, 0
	v_mov_b32_e32 v19, 0
	v_mov_b32_e32 v20, 0
	v_mov_b32_e32 v21, 0
	v_mov_b32_e32 v22, 0
	v_mov_b32_e32 v23, 0
	v_mov_b32_e32 v24, 0
	v_mov_b32_e32 v25, 0
	v_mov_b32_e32 v26, 0
	v_mov_b32_e32 v27, 0
	v_mov_b32_e32 v28, 0
	v_mov_b32_e32 v29, 0
	v_mov_b32_e32 v30, 0
	v_mov_b32_e32 v31, 0
	v_mov_b32_e32 v32, 0
	v_mov_b32_e32 v33, 0
	v_mov_b32_e32 v34, 0
	v_mov_b32_e32 v35, 0
	v_mov_b32_e32 v36, 0
	v_mov_b32_e32 v37, 0
	v_mov_b32_e32 v38, 0
	v_mov_b32_e32 v39, 0
	v_mov_b32_e32 v40, 0
	v_mov_b32_e32 v41, 0
	v_mov_b32_e32 v42, 0
	v_mov_b32_e32 v43, 0
	v_mov_b32_e32 v44, 0
	v_mov_b32_e32 v45, 0
	v_mov_b32_e32 v46, 0
	v_mov_b32_e32 v47, 0
	v_mov_b32_e32 v48, 0
	v_mov_b32_e32 v49, 0
	v_mov_b32_e32 v50, 0
	v_mov_b32_e32 v51, 0
	v_mov_b32_e32 v52, 0
	v_mov_b32_e32 v53, 0
	v_mov_b32_e32 v54, 0
	v_mov_b32_e32 v55, 0
	v_mov_b32_e32 v56, 0
	v_mov_b32_e32 v57, 0
	v_mov_b32_e32 v58, 0
	v_mov_b32_e32 v59, 0
	v_mov_b32_e32 v60, 0
	v_mov_b32_e32 v61, 0
	v_mov_b32_e32 v62, 0
	v_mov_b32_e32 v63, 0
	v_mov_b32_e32 v144, 0
	v_mov_b32_e32 v145, 0
	v_mov_b32_e32 v146, 0
	v_mov_b32_e32 v147, 0
	v_mov_b32_e32 v148, 0
	v_mov_b32_e32 v149, 0
	v_mov_b32_e32 v150, 0
	v_mov_b32_e32 v151, 0
	v_mov_b32_e32 v152, 0
	v_mov_b32_e32 v153, 0
	v_mov_b32_e32 v154, 0
	v_mov_b32_e32 v155, 0
	v_mov_b32_e32 v156, 0
	v_mov_b32_e32 v157, 0
	v_mov_b32_e32 v158, 0
	v_mov_b32_e32 v159, 0
	s_mov_b32 s35, 0
	s_mov_b32 s11, 0
	s_add_i32 s36, s31, 64
	s_mov_b32 s37, s31
	s_lshl_b32 s44, s36, 12
	s_add_u32 s50, s47, s44
	s_addc_u32 s51, s63, 0
	s_add_u32 s52, s50, 0x20000
	s_addc_u32 s53, s51, 0
	s_lshl_b32 s44, s37, 12
	s_add_u32 s54, s47, s44
	s_addc_u32 s55, s63, 0
	s_add_u32 s56, s54, 0x20000
	s_addc_u32 s57, s55, 0
	s_lshl_b32 s44, s36, 10
	s_add_u32 s58, s60, s44
	s_addc_u32 s59, s61, 0
	global_load_dwordx4 v[232:235], v180, s[50:51]
	global_load_dwordx4 v[236:239], v180, s[52:53]
	global_load_dwordx4 v[224:227], v180, s[54:55] offset:256
	global_load_dwordx4 v[228:231], v180, s[56:57] offset:256
	global_load_dwordx4 v[240:243], v181, s[58:59]
	s_cmp_eq_u32 s41, 0
	s_cbranch_scc1 .Lpp_ga
	s_waitcnt vmcnt(0)
	ds_write_b128 v246, v[232:235]
	ds_write_b128 v247, v[236:239]
	ds_write_b128 v248, v[240:243]
	ds_write_b128 v244, v[224:227]
	ds_write_b128 v245, v[228:231]
	v_xor_b32_e32 v244, 0x4000, v244
	v_xor_b32_e32 v245, 0x4000, v245
	v_xor_b32_e32 v246, 0x4000, v246
	v_xor_b32_e32 v247, 0x4000, v247
	v_xor_b32_e32 v248, 0x2000, v248
	s_add_i32 s36, s35, 2
	s_min_u32 s36, s36, 67
	s_lshl_b32 s44, s36, 6
	s_add_i32 s45, s31, s44
	s_add_i32 s46, s24, s44
	s_add_i32 s46, s46, 0xffffff00
	s_cmp_lt_u32 s36, 4
	s_cselect_b32 s36, s45, s46
	s_add_i32 s37, s35, 1
	s_min_u32 s37, s37, 67
	s_lshl_b32 s44, s37, 6
	s_add_i32 s45, s31, s44
	s_add_i32 s46, s24, s44
	s_add_i32 s46, s46, 0xffffff00
	s_cmp_lt_u32 s37, 4
	s_cselect_b32 s37, s45, s46
	s_add_i32 s35, s35, 1
	s_lshl_b32 s44, s36, 12
	s_add_u32 s50, s47, s44
	s_addc_u32 s51, s63, 0
	s_add_u32 s52, s50, 0x20000
	s_addc_u32 s53, s51, 0
	s_lshl_b32 s44, s37, 12
	s_add_u32 s54, s47, s44
	s_addc_u32 s55, s63, 0
	s_add_u32 s56, s54, 0x20000
	s_addc_u32 s57, s55, 0
	s_lshl_b32 s44, s36, 10
	s_add_u32 s58, s60, s44
	s_addc_u32 s59, s61, 0
	global_load_dwordx4 v[232:235], v180, s[50:51]
	global_load_dwordx4 v[236:239], v180, s[52:53]
	global_load_dwordx4 v[224:227], v180, s[54:55] offset:256
	global_load_dwordx4 v[228:231], v180, s[56:57] offset:256
	global_load_dwordx4 v[240:243], v181, s[58:59]
	s_waitcnt lgkmcnt(0)
	s_barrier
; __device__ __forceinline__ void partialSM(f32x16& p0, f32x16& p1, float& m_reg, float& mn, float& alpha) {
;   constexpr float C = SCALE * 1.4426950408889634f;
;   float pmax = p0[0]; for (int r = 1; r < 16; ++r) pmax = fmaxf(pmax, p0[r]); for (int r = 0; r < 16; ++r) pmax = fmaxf(pmax, p1[r]);
;   { auto rr = __builtin_amdgcn_permlane32_swap(__float_as_uint(pmax), __float_as_uint(pmax), false, false);
;     pmax = fmaxf(__uint_as_float(rr[0]), __uint_as_float(rr[1])); }
;   if (__builtin_expect(__all(pmax - m_reg <= THR / SCALE), 1)) { mn = m_reg; alpha = 1.f; }
; __device__ __forceinline__ void qkt(f32x16& p0, f32x16& p1, const char* Kn, const char* Kp, const bf16x8* qr, int r32, int hi) {
;   p0 = f32x16{}; p1 = f32x16{};
; #pragma unroll
;   for (int d0 = 0; d0 < 8; ++d0) { int cb = (d0 * 16 + hi * 8) * 2;
;     bf16x8 b0 = *reinterpret_cast<const bf16x8*>(Kn + KSWZ(r32, cb));
;     bf16x8 b1 = *reinterpret_cast<const bf16x8*>(Kn + KSWZ(32 + r32, cb));
;     p0 = __builtin_amdgcn_mfma_f32_32x32x16_bf16(b0, qr[d0], p0, 0, 0, 0);
;     p1 = __builtin_amdgcn_mfma_f32_32x32x16_bf16(b1, qr[d0], p1, 0, 0, 0); }
; #pragma unroll
;   for (int d1 = 0; d1 < 4; ++d1) { int cb = (d1 * 16 + hi * 8) * 2;
;     bf16x8 b0 = *reinterpret_cast<const bf16x8*>(Kp + KPSWZ(r32, cb));
;     bf16x8 b1 = *reinterpret_cast<const bf16x8*>(Kp + KPSWZ(32 + r32, cb));
;     p0 = __builtin_amdgcn_mfma_f32_32x32x16_bf16(b0, qr[8 + d1], p0, 0, 0, 0);
;     p1 = __builtin_amdgcn_mfma_f32_32x32x16_bf16(b1, qr[8 + d1], p1, 0, 0, 0); }
.Lpp_ga:
	ds_read_b128 v[192:195], v160
	ds_read_b128 v[196:199], v160 offset:8192
	ds_read_b128 v[200:203], v161
	ds_read_b128 v[204:207], v161 offset:8192
	ds_read_b128 v[208:211], v162
	ds_read_b128 v[212:215], v162 offset:8192
	ds_read_b128 v[216:219], v163
	ds_read_b128 v[220:223], v163 offset:8192
	s_waitcnt lgkmcnt(6)
	v_mfma_f32_32x32x16_bf16 v[80:95], v[192:195], v[136:139], 0
	ds_read_b128 v[192:195], v164
	v_mfma_f32_32x32x16_bf16 v[64:79], v[196:199], v[136:139], 0
	ds_read_b128 v[196:199], v164 offset:8192
	s_waitcnt lgkmcnt(6)
	v_mfma_f32_32x32x16_bf16 v[80:95], v[200:203], v[132:135], v[80:95]
	ds_read_b128 v[200:203], v165
	v_mfma_f32_32x32x16_bf16 v[64:79], v[204:207], v[132:135], v[64:79]
	ds_read_b128 v[204:207], v165 offset:8192
	s_waitcnt lgkmcnt(6)
	v_mfma_f32_32x32x16_bf16 v[80:95], v[208:211], v[128:131], v[80:95]
	ds_read_b128 v[208:211], v166
	v_mfma_f32_32x32x16_bf16 v[64:79], v[212:215], v[128:131], v[64:79]
	ds_read_b128 v[212:215], v166 offset:8192
	s_waitcnt lgkmcnt(6)
	v_mfma_f32_32x32x16_bf16 v[80:95], v[216:219], v[124:127], v[80:95]
	ds_read_b128 v[216:219], v167
	v_mfma_f32_32x32x16_bf16 v[64:79], v[220:223], v[124:127], v[64:79]
	ds_read_b128 v[220:223], v167 offset:8192
	s_waitcnt lgkmcnt(6)
	v_mfma_f32_32x32x16_bf16 v[80:95], v[192:195], v[120:123], v[80:95]
	ds_read_b128 v[192:195], v168
	v_mfma_f32_32x32x16_bf16 v[64:79], v[196:199], v[120:123], v[64:79]
	ds_read_b128 v[196:199], v168 offset:4096
	s_waitcnt lgkmcnt(6)
	v_mfma_f32_32x32x16_bf16 v[80:95], v[200:203], v[140:143], v[80:95]
	ds_read_b128 v[200:203], v169
	v_mfma_f32_32x32x16_bf16 v[64:79], v[204:207], v[140:143], v[64:79]
	ds_read_b128 v[204:207], v169 offset:4096
	s_waitcnt lgkmcnt(6)
	v_mfma_f32_32x32x16_bf16 v[80:95], v[208:211], v[116:119], v[80:95]
	ds_read_b128 v[208:211], v170
	v_mfma_f32_32x32x16_bf16 v[64:79], v[212:215], v[116:119], v[64:79]
	ds_read_b128 v[212:215], v170 offset:4096
	s_waitcnt lgkmcnt(6)
	v_mfma_f32_32x32x16_bf16 v[80:95], v[216:219], v[112:115], v[80:95]
	ds_read_b128 v[216:219], v171
	v_mfma_f32_32x32x16_bf16 v[64:79], v[220:223], v[112:115], v[64:79]
	ds_read_b128 v[220:223], v171 offset:4096
	s_waitcnt lgkmcnt(6)
	v_mfma_f32_32x32x16_bf16 v[80:95], v[192:195], v[108:111], v[80:95]
	v_mfma_f32_32x32x16_bf16 v[64:79], v[196:199], v[108:111], v[64:79]
	s_waitcnt lgkmcnt(4)
	v_mfma_f32_32x32x16_bf16 v[80:95], v[200:203], v[104:107], v[80:95]
	v_mfma_f32_32x32x16_bf16 v[64:79], v[204:207], v[104:107], v[64:79]
	s_waitcnt lgkmcnt(2)
	v_mfma_f32_32x32x16_bf16 v[80:95], v[208:211], v[100:103], v[80:95]
	v_mfma_f32_32x32x16_bf16 v[64:79], v[212:215], v[100:103], v[64:79]
	s_waitcnt lgkmcnt(0)
	v_mfma_f32_32x32x16_bf16 v[80:95], v[216:219], v[96:99], v[80:95]
	v_mfma_f32_32x32x16_bf16 v[64:79], v[220:223], v[96:99], v[64:79]
	s_barrier
.Lpp_loop:
	s_waitcnt vmcnt(0)
	ds_write_b128 v246, v[232:235]
	ds_write_b128 v247, v[236:239]
	ds_write_b128 v248, v[240:243]
	ds_write_b128 v244, v[224:227]
	ds_write_b128 v245, v[228:231]
	v_xor_b32_e32 v244, 0x4000, v244
	v_xor_b32_e32 v245, 0x4000, v245
	v_xor_b32_e32 v246, 0x4000, v246
	v_xor_b32_e32 v247, 0x4000, v247
	v_xor_b32_e32 v248, 0x2000, v248
	s_add_i32 s36, s35, 2
	s_min_u32 s36, s36, 67
	s_lshl_b32 s44, s36, 6
	s_add_i32 s45, s31, s44
	s_add_i32 s46, s24, s44
	s_add_i32 s46, s46, 0xffffff00
	s_cmp_lt_u32 s36, 4
	s_cselect_b32 s36, s45, s46
	s_add_i32 s37, s35, 1
	s_min_u32 s37, s37, 67
	s_lshl_b32 s44, s37, 6
	s_add_i32 s45, s31, s44
	s_add_i32 s46, s24, s44
	s_add_i32 s46, s46, 0xffffff00
	s_cmp_lt_u32 s37, 4
	s_cselect_b32 s37, s45, s46
	s_add_i32 s35, s35, 1
	s_lshl_b32 s44, s36, 12
	s_add_u32 s50, s47, s44
	s_addc_u32 s51, s63, 0
	s_add_u32 s52, s50, 0x20000
	s_addc_u32 s53, s51, 0
	s_lshl_b32 s44, s37, 12
	s_add_u32 s54, s47, s44
	s_addc_u32 s55, s63, 0
	s_add_u32 s56, s54, 0x20000
	s_addc_u32 s57, s55, 0
	s_lshl_b32 s44, s36, 10
	s_add_u32 s58, s60, s44
	s_addc_u32 s59, s61, 0
	global_load_dwordx4 v[232:235], v180, s[50:51]
	global_load_dwordx4 v[236:239], v180, s[52:53]
	global_load_dwordx4 v[224:227], v180, s[54:55] offset:256
	global_load_dwordx4 v[228:231], v180, s[56:57] offset:256
	global_load_dwordx4 v[240:243], v181, s[58:59]
	s_cmp_lg_u32 s62, 0
	s_cbranch_scc1 .Lpp_safe_a
	v_max3_f32 v250, v80, v81, v82
	v_max3_f32 v250, v250, v83, v84
	v_max3_f32 v250, v250, v85, v86
	v_max3_f32 v250, v250, v87, v88
	v_max3_f32 v250, v250, v89, v90
	v_max3_f32 v250, v250, v91, v92
	v_max3_f32 v250, v250, v93, v94
	v_max3_f32 v250, v250, v95, v64
	v_max3_f32 v250, v250, v65, v66
	v_max3_f32 v250, v250, v67, v68
	v_max3_f32 v250, v250, v69, v70
	v_max3_f32 v250, v250, v71, v72
	v_max3_f32 v250, v250, v73, v74
	v_max3_f32 v250, v250, v75, v76
	v_max3_f32 v250, v250, v77, v78
	v_max3_f32 v250, v250, v79, v79
	v_cmp_lt_f32_e64 vcc, s64, |v250|
	s_nop 4
	s_cbranch_vccnz .Lpp_sw_a
; __device__ __forceinline__ void partialSM(f32x16& p0, f32x16& p1, float& m_reg, float& mn, float& alpha) {
;   constexpr float C = SCALE * 1.4426950408889634f;
;   float pmax = p0[0]; for (int r = 1; r < 16; ++r) pmax = fmaxf(pmax, p0[r]); for (int r = 0; r < 16; ++r) pmax = fmaxf(pmax, p1[r]);
;   { auto rr = __builtin_amdgcn_permlane32_swap(__float_as_uint(pmax), __float_as_uint(pmax), false, false);
;     pmax = fmaxf(__uint_as_float(rr[0]), __uint_as_float(rr[1])); }
;   if (__builtin_expect(__all(pmax - m_reg <= THR / SCALE), 1)) { mn = m_reg; alpha = 1.f; }
;   else { mn = fmaxf(m_reg, pmax); alpha = __builtin_amdgcn_exp2f((m_reg - mn) * C); m_reg = mn; }
;   float mnC = -mn * C;
;   for (int r = 0; r < 16; ++r) p0[r] = fmaf(p0[r], C, mnC); for (int r = 0; r < 16; ++r) p1[r] = fmaf(p1[r], C, mnC);
;   for (int r = 0; r < 16; ++r) p0[r] = __builtin_amdgcn_exp2f(p0[r]);
; }
; __device__ __forceinline__ void finishSM(f32x16& p0, f32x16& p1, float alpha, float& l_reg, bf16x8& pa0, bf16x8& pa1, bf16x8& pa2, bf16x8& pa3) {
;   for (int r = 0; r < 16; ++r) p1[r] = __builtin_amdgcn_exp2f(p1[r]);
;   float ps = 0; for (int r = 0; r < 16; ++r) ps += p0[r]; for (int r = 0; r < 16; ++r) ps += p1[r];
;   { auto rr = __builtin_amdgcn_permlane32_swap(__float_as_uint(ps), __float_as_uint(ps), false, false);
;     ps = __uint_as_float(rr[0]) + __uint_as_float(rr[1]); }
;   l_reg = l_reg * alpha + ps;
	v_exp_f32_e32 v80, v80
	v_exp_f32_e32 v81, v81
	v_exp_f32_e32 v82, v82
	v_exp_f32_e32 v83, v83
	v_exp_f32_e32 v84, v84
	v_exp_f32_e32 v85, v85
	v_exp_f32_e32 v86, v86
	v_exp_f32_e32 v87, v87
	v_exp_f32_e32 v88, v88
	v_exp_f32_e32 v89, v89
	v_exp_f32_e32 v90, v90
	v_exp_f32_e32 v91, v91
	v_exp_f32_e32 v92, v92
	v_exp_f32_e32 v93, v93
	v_exp_f32_e32 v94, v94
	v_exp_f32_e32 v95, v95
	v_exp_f32_e32 v64, v64
	v_exp_f32_e32 v65, v65
	v_exp_f32_e32 v66, v66
	v_exp_f32_e32 v67, v67
	v_exp_f32_e32 v68, v68
	v_exp_f32_e32 v69, v69
	v_exp_f32_e32 v70, v70
	v_exp_f32_e32 v71, v71
	v_exp_f32_e32 v72, v72
	v_exp_f32_e32 v73, v73
	v_exp_f32_e32 v74, v74
	v_exp_f32_e32 v75, v75
	v_exp_f32_e32 v76, v76
	v_exp_f32_e32 v77, v77
	v_exp_f32_e32 v78, v78
	v_exp_f32_e32 v79, v79
	s_nop 0
	v_add_f32_e32 v249, v80, v81
	v_add_f32_e32 v249, v82, v249
	v_add_f32_e32 v249, v83, v249
	v_add_f32_e32 v249, v84, v249
	v_add_f32_e32 v249, v85, v249
	v_add_f32_e32 v249, v86, v249
	v_add_f32_e32 v249, v87, v249
	v_add_f32_e32 v249, v88, v249
	v_add_f32_e32 v249, v89, v249
	v_add_f32_e32 v249, v90, v249
	v_add_f32_e32 v249, v91, v249
	v_add_f32_e32 v249, v92, v249
	v_add_f32_e32 v249, v93, v249
	v_add_f32_e32 v249, v94, v249
	v_add_f32_e32 v249, v95, v249
	v_add_f32_e32 v249, v64, v249
	v_add_f32_e32 v249, v65, v249
	v_add_f32_e32 v249, v66, v249
	v_add_f32_e32 v249, v67, v249
	v_add_f32_e32 v249, v68, v249
	v_add_f32_e32 v249, v69, v249
	v_add_f32_e32 v249, v70, v249
	v_add_f32_e32 v249, v71, v249
	v_add_f32_e32 v249, v72, v249
	v_add_f32_e32 v249, v73, v249
	v_add_f32_e32 v249, v74, v249
	v_add_f32_e32 v249, v75, v249
	v_add_f32_e32 v249, v76, v249
	v_add_f32_e32 v249, v77, v249
	v_add_f32_e32 v249, v78, v249
	v_add_f32_e32 v249, v79, v249
	v_add_f32_e32 v176, v176, v249
	v_cvt_pk_bf16_f32 v144, v80, v81
	v_cvt_pk_bf16_f32 v145, v82, v83
	v_cvt_pk_bf16_f32 v146, v84, v85
	v_cvt_pk_bf16_f32 v147, v86, v87
	v_cvt_pk_bf16_f32 v148, v88, v89
	v_cvt_pk_bf16_f32 v149, v90, v91
	v_cvt_pk_bf16_f32 v150, v92, v93
	v_cvt_pk_bf16_f32 v151, v94, v95
	v_cvt_pk_bf16_f32 v152, v64, v65
	v_cvt_pk_bf16_f32 v153, v66, v67
	v_cvt_pk_bf16_f32 v154, v68, v69
	v_cvt_pk_bf16_f32 v155, v70, v71
	v_cvt_pk_bf16_f32 v156, v72, v73
	v_cvt_pk_bf16_f32 v157, v74, v75
	v_cvt_pk_bf16_f32 v158, v76, v77
	v_cvt_pk_bf16_f32 v159, v78, v79
	s_nop 1
	v_permlane32_swap_b32_e32 v144, v146
	v_permlane32_swap_b32_e32 v145, v147
	v_permlane32_swap_b32_e32 v148, v150
	v_permlane32_swap_b32_e32 v149, v151
	v_permlane32_swap_b32_e32 v152, v154
	v_permlane32_swap_b32_e32 v153, v155
	v_permlane32_swap_b32_e32 v156, v158
	v_permlane32_swap_b32_e32 v157, v159
	s_branch .Lpp_send_a
.Lpp_sw_a:
	v_mov_b32_e32 v250, v176
	s_nop 1
	v_permlane32_swap_b32_e32 v176, v250
	v_add_f32_e32 v176, v176, v250
	v_cmp_eq_f32_e32 vcc, 0, v176
	v_mov_b32_e32 v251, 0xf149f2ca
	s_nop 1
	v_cndmask_b32_e32 v175, v175, v251, vcc
	s_mov_b32 s62, 1
.Lpp_safe_a:
	v_max3_f32 v250, v80, v81, v82
	v_max3_f32 v250, v250, v83, v84
	v_max3_f32 v250, v250, v85, v86
	v_max3_f32 v250, v250, v87, v88
	v_max3_f32 v250, v250, v89, v90
	v_max3_f32 v250, v250, v91, v92
	v_max3_f32 v250, v250, v93, v94
	v_max3_f32 v250, v250, v95, v64
	v_max3_f32 v250, v250, v65, v66
	v_max3_f32 v250, v250, v67, v68
	v_max3_f32 v250, v250, v69, v70
	v_max3_f32 v250, v250, v71, v72
	v_max3_f32 v250, v250, v73, v74
	v_max3_f32 v250, v250, v75, v76
	v_max3_f32 v250, v250, v77, v78
	v_max3_f32 v250, v250, v79, v79
	v_mov_b32_e32 v251, v250
	s_nop 1
	v_permlane32_swap_b32_e32 v250, v251
	v_max_f32_e32 v250, v250, v251
	v_sub_f32_e32 v251, v250, v175
	v_cmp_ge_f32_e32 vcc, 0x4138aa3b, v251
	v_max_f32_e32 v249, v175, v250
	v_sub_f32_e32 v251, v175, v249
	v_exp_f32_e32 v251, v251
	s_nop 1
	s_cmp_eq_u64 vcc, exec
	s_cselect_b64 s[8:9], -1, 0
	v_cndmask_b32_e64 v177, v251, 1.0, s[8:9]
	v_cndmask_b32_e64 v175, v249, v175, s[8:9]
	v_cmp_gt_f32_e32 vcc, 1.0, v177
	s_nop 4
	s_cbranch_vccz .Lpp_nr_a
	s_and_saveexec_b64 s[42:43], s[6:7]
	ds_write_b32 v186, v177 offset:128
	s_or_b64 exec, exec, s[42:43]
	s_waitcnt lgkmcnt(0)
	v_add_u32_e32 v187, v179, v172
	ds_read_b128 v[192:195], v187 offset:128
	ds_read_b128 v[196:199], v187 offset:160
	ds_read_b128 v[200:203], v187 offset:192
	ds_read_b128 v[204:207], v187 offset:224
	s_waitcnt lgkmcnt(0)
	v_pk_mul_f32 v[0:1], v[0:1], v[192:193]
	v_pk_mul_f32 v[2:3], v[2:3], v[194:195]
	v_pk_mul_f32 v[4:5], v[4:5], v[196:197]
	v_pk_mul_f32 v[6:7], v[6:7], v[198:199]
	v_pk_mul_f32 v[8:9], v[8:9], v[200:201]
	v_pk_mul_f32 v[10:11], v[10:11], v[202:203]
	v_pk_mul_f32 v[12:13], v[12:13], v[204:205]
	v_pk_mul_f32 v[14:15], v[14:15], v[206:207]
	v_pk_mul_f32 v[48:49], v[48:49], v[192:193]
	v_pk_mul_f32 v[50:51], v[50:51], v[194:195]
	v_pk_mul_f32 v[52:53], v[52:53], v[196:197]
	v_pk_mul_f32 v[54:55], v[54:55], v[198:199]
	v_pk_mul_f32 v[56:57], v[56:57], v[200:201]
	v_pk_mul_f32 v[58:59], v[58:59], v[202:203]
	v_pk_mul_f32 v[60:61], v[60:61], v[204:205]
	v_pk_mul_f32 v[62:63], v[62:63], v[206:207]
	v_pk_mul_f32 v[32:33], v[32:33], v[192:193]
	v_pk_mul_f32 v[34:35], v[34:35], v[194:195]
	v_pk_mul_f32 v[36:37], v[36:37], v[196:197]
	v_pk_mul_f32 v[38:39], v[38:39], v[198:199]
	v_pk_mul_f32 v[40:41], v[40:41], v[200:201]
	v_pk_mul_f32 v[42:43], v[42:43], v[202:203]
	v_pk_mul_f32 v[44:45], v[44:45], v[204:205]
	v_pk_mul_f32 v[46:47], v[46:47], v[206:207]
	v_pk_mul_f32 v[16:17], v[16:17], v[192:193]
	v_pk_mul_f32 v[18:19], v[18:19], v[194:195]
	v_pk_mul_f32 v[20:21], v[20:21], v[196:197]
	v_pk_mul_f32 v[22:23], v[22:23], v[198:199]
	v_pk_mul_f32 v[24:25], v[24:25], v[200:201]
	v_pk_mul_f32 v[26:27], v[26:27], v[202:203]
	v_pk_mul_f32 v[28:29], v[28:29], v[204:205]
	v_pk_mul_f32 v[30:31], v[30:31], v[206:207]
; __device__ __forceinline__ void partialSM(f32x16& p0, f32x16& p1, float& m_reg, float& mn, float& alpha) {
;     ...
;   float mnC = -mn * C;
;   for (int r = 0; r < 16; ++r) p0[r] = fmaf(p0[r], C, mnC); for (int r = 0; r < 16; ++r) p1[r] = fmaf(p1[r], C, mnC);
;   for (int r = 0; r < 16; ++r) p0[r] = __builtin_amdgcn_exp2f(p0[r]);
; }
; __device__ __forceinline__ void finishSM(f32x16& p0, f32x16& p1, float alpha, float& l_reg, bf16x8& pa0, bf16x8& pa1, bf16x8& pa2, bf16x8& pa3) {
;   for (int r = 0; r < 16; ++r) p1[r] = __builtin_amdgcn_exp2f(p1[r]);
;   float ps = 0; for (int r = 0; r < 16; ++r) ps += p0[r]; for (int r = 0; r < 16; ++r) ps += p1[r];
;   { auto rr = __builtin_amdgcn_permlane32_swap(__float_as_uint(ps), __float_as_uint(ps), false, false);
;     ps = __uint_as_float(rr[0]) + __uint_as_float(rr[1]); }
;   l_reg = l_reg * alpha + ps;
;     ...
;   PK4(p0, 0, pa0); PK4(p0, 8, pa1); PK4(p1, 0, pa2); PK4(p1, 8, pa3);
; __device__ __forceinline__ void qkt(f32x16& p0, f32x16& p1, const char* Kn, const char* Kp, const bf16x8* qr, int r32, int hi) {
;   p0 = f32x16{}; p1 = f32x16{};
; #pragma unroll
;   for (int d0 = 0; d0 < 8; ++d0) { int cb = (d0 * 16 + hi * 8) * 2;
;     bf16x8 b0 = *reinterpret_cast<const bf16x8*>(Kn + KSWZ(r32, cb));
;     bf16x8 b1 = *reinterpret_cast<const bf16x8*>(Kn + KSWZ(32 + r32, cb));
;     p0 = __builtin_amdgcn_mfma_f32_32x32x16_bf16(b0, qr[d0], p0, 0, 0, 0);
;     p1 = __builtin_amdgcn_mfma_f32_32x32x16_bf16(b1, qr[d0], p1, 0, 0, 0); }
; #pragma unroll
;   for (int d1 = 0; d1 < 4; ++d1) { int cb = (d1 * 16 + hi * 8) * 2;
;     bf16x8 b0 = *reinterpret_cast<const bf16x8*>(Kp + KPSWZ(r32, cb));
;     bf16x8 b1 = *reinterpret_cast<const bf16x8*>(Kp + KPSWZ(32 + r32, cb));
;     p0 = __builtin_amdgcn_mfma_f32_32x32x16_bf16(b0, qr[8 + d1], p0, 0, 0, 0);
;     p1 = __builtin_amdgcn_mfma_f32_32x32x16_bf16(b1, qr[8 + d1], p1, 0, 0, 0); }
.Lpp_nr_a:
	v_sub_f32_e32 v80, v80, v175
	v_sub_f32_e32 v81, v81, v175
	v_sub_f32_e32 v82, v82, v175
	v_sub_f32_e32 v83, v83, v175
	v_sub_f32_e32 v84, v84, v175
	v_sub_f32_e32 v85, v85, v175
	v_sub_f32_e32 v86, v86, v175
	v_sub_f32_e32 v87, v87, v175
	v_sub_f32_e32 v88, v88, v175
	v_sub_f32_e32 v89, v89, v175
	v_sub_f32_e32 v90, v90, v175
	v_sub_f32_e32 v91, v91, v175
	v_sub_f32_e32 v92, v92, v175
	v_sub_f32_e32 v93, v93, v175
	v_sub_f32_e32 v94, v94, v175
	v_sub_f32_e32 v95, v95, v175
	v_sub_f32_e32 v64, v64, v175
	v_sub_f32_e32 v65, v65, v175
	v_sub_f32_e32 v66, v66, v175
	v_sub_f32_e32 v67, v67, v175
	v_sub_f32_e32 v68, v68, v175
	v_sub_f32_e32 v69, v69, v175
	v_sub_f32_e32 v70, v70, v175
	v_sub_f32_e32 v71, v71, v175
	v_sub_f32_e32 v72, v72, v175
	v_sub_f32_e32 v73, v73, v175
	v_sub_f32_e32 v74, v74, v175
	v_sub_f32_e32 v75, v75, v175
	v_sub_f32_e32 v76, v76, v175
	v_sub_f32_e32 v77, v77, v175
	v_sub_f32_e32 v78, v78, v175
	v_sub_f32_e32 v79, v79, v175
	v_exp_f32_e32 v80, v80
	v_exp_f32_e32 v81, v81
	v_exp_f32_e32 v82, v82
	v_exp_f32_e32 v83, v83
	v_exp_f32_e32 v84, v84
	v_exp_f32_e32 v85, v85
	v_exp_f32_e32 v86, v86
	v_exp_f32_e32 v87, v87
	v_exp_f32_e32 v88, v88
	v_exp_f32_e32 v89, v89
	v_exp_f32_e32 v90, v90
	v_exp_f32_e32 v91, v91
	v_exp_f32_e32 v92, v92
	v_exp_f32_e32 v93, v93
	v_exp_f32_e32 v94, v94
	v_exp_f32_e32 v95, v95
	v_exp_f32_e32 v64, v64
	v_exp_f32_e32 v65, v65
	v_exp_f32_e32 v66, v66
	v_exp_f32_e32 v67, v67
	v_exp_f32_e32 v68, v68
	v_exp_f32_e32 v69, v69
	v_exp_f32_e32 v70, v70
	v_exp_f32_e32 v71, v71
	v_exp_f32_e32 v72, v72
	v_exp_f32_e32 v73, v73
	v_exp_f32_e32 v74, v74
	v_exp_f32_e32 v75, v75
	v_exp_f32_e32 v76, v76
	v_exp_f32_e32 v77, v77
	v_exp_f32_e32 v78, v78
	v_exp_f32_e32 v79, v79
	s_nop 0
	v_add_f32_e32 v249, v80, v81
	v_add_f32_e32 v249, v82, v249
	v_add_f32_e32 v249, v83, v249
	v_add_f32_e32 v249, v84, v249
	v_add_f32_e32 v249, v85, v249
	v_add_f32_e32 v249, v86, v249
	v_add_f32_e32 v249, v87, v249
	v_add_f32_e32 v249, v88, v249
	v_add_f32_e32 v249, v89, v249
	v_add_f32_e32 v249, v90, v249
	v_add_f32_e32 v249, v91, v249
	v_add_f32_e32 v249, v92, v249
	v_add_f32_e32 v249, v93, v249
	v_add_f32_e32 v249, v94, v249
	v_add_f32_e32 v249, v95, v249
	v_add_f32_e32 v249, v64, v249
	v_add_f32_e32 v249, v65, v249
	v_add_f32_e32 v249, v66, v249
	v_add_f32_e32 v249, v67, v249
	v_add_f32_e32 v249, v68, v249
	v_add_f32_e32 v249, v69, v249
	v_add_f32_e32 v249, v70, v249
	v_add_f32_e32 v249, v71, v249
	v_add_f32_e32 v249, v72, v249
	v_add_f32_e32 v249, v73, v249
	v_add_f32_e32 v249, v74, v249
	v_add_f32_e32 v249, v75, v249
	v_add_f32_e32 v249, v76, v249
	v_add_f32_e32 v249, v77, v249
	v_add_f32_e32 v249, v78, v249
	v_add_f32_e32 v249, v79, v249
	v_mov_b32_e32 v250, v249
	s_nop 1
	v_permlane32_swap_b32_e32 v249, v250
	v_add_f32_e32 v249, v249, v250
	v_fma_f32 v176, v176, v177, v249
	v_cvt_pk_bf16_f32 v144, v80, v81
	v_cvt_pk_bf16_f32 v145, v82, v83
	v_cvt_pk_bf16_f32 v146, v84, v85
	v_cvt_pk_bf16_f32 v147, v86, v87
	v_cvt_pk_bf16_f32 v148, v88, v89
	v_cvt_pk_bf16_f32 v149, v90, v91
	v_cvt_pk_bf16_f32 v150, v92, v93
	v_cvt_pk_bf16_f32 v151, v94, v95
	v_cvt_pk_bf16_f32 v152, v64, v65
	v_cvt_pk_bf16_f32 v153, v66, v67
	v_cvt_pk_bf16_f32 v154, v68, v69
	v_cvt_pk_bf16_f32 v155, v70, v71
	v_cvt_pk_bf16_f32 v156, v72, v73
	v_cvt_pk_bf16_f32 v157, v74, v75
	v_cvt_pk_bf16_f32 v158, v76, v77
	v_cvt_pk_bf16_f32 v159, v78, v79
	s_nop 1
	v_permlane32_swap_b32_e32 v144, v146
	v_permlane32_swap_b32_e32 v145, v147
	v_permlane32_swap_b32_e32 v148, v150
	v_permlane32_swap_b32_e32 v149, v151
	v_permlane32_swap_b32_e32 v152, v154
	v_permlane32_swap_b32_e32 v153, v155
	v_permlane32_swap_b32_e32 v156, v158
	v_permlane32_swap_b32_e32 v157, v159
.Lpp_send_a:
	s_waitcnt lgkmcnt(0)
	s_barrier
	s_add_i32 s11, s11, 1
	ds_read_b128 v[192:195], v160 offset:16384
	ds_read_b128 v[196:199], v160 offset:24576
	ds_read_b128 v[200:203], v161 offset:16384
	ds_read_b128 v[204:207], v161 offset:24576
	ds_read_b128 v[208:211], v162 offset:16384
	ds_read_b128 v[212:215], v162 offset:24576
	ds_read_b128 v[216:219], v163 offset:16384
	ds_read_b128 v[220:223], v163 offset:24576
	s_waitcnt lgkmcnt(6)
	v_mfma_f32_32x32x16_bf16 v[80:95], v[192:195], v[136:139], 0
	ds_read_b128 v[192:195], v164 offset:16384
	v_mfma_f32_32x32x16_bf16 v[64:79], v[196:199], v[136:139], 0
	ds_read_b128 v[196:199], v164 offset:24576
	s_waitcnt lgkmcnt(6)
	v_mfma_f32_32x32x16_bf16 v[80:95], v[200:203], v[132:135], v[80:95]
	ds_read_b128 v[200:203], v165 offset:16384
	v_mfma_f32_32x32x16_bf16 v[64:79], v[204:207], v[132:135], v[64:79]
	ds_read_b128 v[204:207], v165 offset:24576
	s_waitcnt lgkmcnt(6)
	v_mfma_f32_32x32x16_bf16 v[80:95], v[208:211], v[128:131], v[80:95]
	ds_read_b128 v[208:211], v166 offset:16384
	v_mfma_f32_32x32x16_bf16 v[64:79], v[212:215], v[128:131], v[64:79]
	ds_read_b128 v[212:215], v166 offset:24576
	s_waitcnt lgkmcnt(6)
	v_mfma_f32_32x32x16_bf16 v[80:95], v[216:219], v[124:127], v[80:95]
	ds_read_b128 v[216:219], v167 offset:16384
	v_mfma_f32_32x32x16_bf16 v[64:79], v[220:223], v[124:127], v[64:79]
	ds_read_b128 v[220:223], v167 offset:24576
	s_waitcnt lgkmcnt(6)
	v_mfma_f32_32x32x16_bf16 v[80:95], v[192:195], v[120:123], v[80:95]
	ds_read_b128 v[192:195], v168 offset:8192
	v_mfma_f32_32x32x16_bf16 v[64:79], v[196:199], v[120:123], v[64:79]
	ds_read_b128 v[196:199], v168 offset:12288
	s_waitcnt lgkmcnt(6)
	v_mfma_f32_32x32x16_bf16 v[80:95], v[200:203], v[140:143], v[80:95]
	ds_read_b128 v[200:203], v169 offset:8192
	v_mfma_f32_32x32x16_bf16 v[64:79], v[204:207], v[140:143], v[64:79]
	ds_read_b128 v[204:207], v169 offset:12288
	s_waitcnt lgkmcnt(6)
; #define SBAR() __builtin_amdgcn_sched_barrier(0)
; __device__ __forceinline__ void qkt(f32x16& p0, f32x16& p1, const char* Kn, const char* Kp, const bf16x8* qr, int r32, int hi) {
;   p0 = f32x16{}; p1 = f32x16{};
; #pragma unroll
;   for (int d0 = 0; d0 < 8; ++d0) { int cb = (d0 * 16 + hi * 8) * 2;
;     bf16x8 b0 = *reinterpret_cast<const bf16x8*>(Kn + KSWZ(r32, cb));
;     bf16x8 b1 = *reinterpret_cast<const bf16x8*>(Kn + KSWZ(32 + r32, cb));
;     p0 = __builtin_amdgcn_mfma_f32_32x32x16_bf16(b0, qr[d0], p0, 0, 0, 0);
;     p1 = __builtin_amdgcn_mfma_f32_32x32x16_bf16(b1, qr[d0], p1, 0, 0, 0); }
; #pragma unroll
;   for (int d1 = 0; d1 < 4; ++d1) { int cb = (d1 * 16 + hi * 8) * 2;
;     bf16x8 b0 = *reinterpret_cast<const bf16x8*>(Kp + KPSWZ(r32, cb));
;     bf16x8 b1 = *reinterpret_cast<const bf16x8*>(Kp + KPSWZ(32 + r32, cb));
;     p0 = __builtin_amdgcn_mfma_f32_32x32x16_bf16(b0, qr[8 + d1], p0, 0, 0, 0);
;     p1 = __builtin_amdgcn_mfma_f32_32x32x16_bf16(b1, qr[8 + d1], p1, 0, 0, 0); }
; template <int D0> __device__ __forceinline__ void pv_one(f32x16& od, int vb, bf16x8 pa0, bf16x8 pa1, bf16x8 pa2, bf16x8 pa3) {
;   const s16x4 l0 = tr_read<v_rd_off(D0, 0, 0)>(vb), h0 = tr_read<v_rd_off(D0, 0, 1)>(vb), l1 = tr_read<v_rd_off(D0, 1, 0)>(vb), h1 = tr_read<v_rd_off(D0, 1, 1)>(vb);
;   const s16x4 l2 = tr_read<v_rd_off(D0, 2, 0)>(vb), h2 = tr_read<v_rd_off(D0, 2, 1)>(vb), l3 = tr_read<v_rd_off(D0, 3, 0)>(vb), h3 = tr_read<v_rd_off(D0, 3, 1)>(vb);
;   asm volatile("s_waitcnt lgkmcnt(0)" ::: "memory"); SBAR();
;     ...
;   od = __builtin_amdgcn_mfma_f32_32x32x16_bf16(pa0, PK(l0, h0), od, 0, 0, 0);
;   od = __builtin_amdgcn_mfma_f32_32x32x16_bf16(pa1, PK(l1, h1), od, 0, 0, 0);
;   od = __builtin_amdgcn_mfma_f32_32x32x16_bf16(pa2, PK(l2, h2), od, 0, 0, 0);
;   od = __builtin_amdgcn_mfma_f32_32x32x16_bf16(pa3, PK(l3, h3), od, 0, 0, 0);
;     ...
; }
; __device__ __forceinline__ void pv_d0(f32x16* o, int vb, bf16x8 pa0, bf16x8 pa1, bf16x8 pa2, bf16x8 pa3) {
;   pv_one<0>(o[0], vb, pa0, pa1, pa2, pa3); pv_one<1>(o[1], vb, pa0, pa1, pa2, pa3); pv_one<2>(o[2], vb, pa0, pa1, pa2, pa3); pv_one<3>(o[3], vb, pa0, pa1, pa2, pa3);
	v_mfma_f32_32x32x16_bf16 v[80:95], v[208:211], v[116:119], v[80:95]
	ds_read_b128 v[208:211], v170 offset:8192
	v_mfma_f32_32x32x16_bf16 v[64:79], v[212:215], v[116:119], v[64:79]
	ds_read_b128 v[212:215], v170 offset:12288
	s_waitcnt lgkmcnt(6)
	v_mfma_f32_32x32x16_bf16 v[80:95], v[216:219], v[112:115], v[80:95]
	ds_read_b128 v[216:219], v171 offset:8192
	v_mfma_f32_32x32x16_bf16 v[64:79], v[220:223], v[112:115], v[64:79]
	ds_read_b128 v[220:223], v171 offset:12288
	s_waitcnt lgkmcnt(6)
	v_mfma_f32_32x32x16_bf16 v[80:95], v[192:195], v[108:111], v[80:95]
	ds_read_b64_tr_b16 v[192:193], v174 offset:0
	ds_read_b64_tr_b16 v[194:195], v174 offset:2048
	v_mfma_f32_32x32x16_bf16 v[64:79], v[196:199], v[108:111], v[64:79]
	ds_read_b64_tr_b16 v[196:197], v174 offset:4096
	ds_read_b64_tr_b16 v[198:199], v174 offset:6144
	s_waitcnt lgkmcnt(8)
	v_mfma_f32_32x32x16_bf16 v[80:95], v[200:203], v[104:107], v[80:95]
	ds_read_b64_tr_b16 v[200:201], v174 offset:8192
	ds_read_b64_tr_b16 v[202:203], v174 offset:10240
	v_mfma_f32_32x32x16_bf16 v[64:79], v[204:207], v[104:107], v[64:79]
	ds_read_b64_tr_b16 v[204:205], v174 offset:12288
	ds_read_b64_tr_b16 v[206:207], v174 offset:14336
	s_waitcnt lgkmcnt(10)
	v_mfma_f32_32x32x16_bf16 v[80:95], v[208:211], v[100:103], v[80:95]
	ds_read_b64_tr_b16 v[208:209], v174 offset:512
	ds_read_b64_tr_b16 v[210:211], v174 offset:2560
	v_mfma_f32_32x32x16_bf16 v[64:79], v[212:215], v[100:103], v[64:79]
	ds_read_b64_tr_b16 v[212:213], v174 offset:4608
	ds_read_b64_tr_b16 v[214:215], v174 offset:6656
	s_waitcnt lgkmcnt(12)
	v_mfma_f32_32x32x16_bf16 v[80:95], v[216:219], v[96:99], v[80:95]
	ds_read_b64_tr_b16 v[216:217], v174 offset:8704
	ds_read_b64_tr_b16 v[218:219], v174 offset:10752
	v_mfma_f32_32x32x16_bf16 v[64:79], v[220:223], v[96:99], v[64:79]
	ds_read_b64_tr_b16 v[220:221], v174 offset:12800
	ds_read_b64_tr_b16 v[222:223], v174 offset:14848
	s_waitcnt lgkmcnt(12)
	v_mfma_f32_32x32x16_bf16 v[0:15], v[144:147], v[192:195], v[0:15]
	ds_read_b64_tr_b16 v[192:193], v174 offset:1024
	ds_read_b64_tr_b16 v[194:195], v174 offset:3072
	v_mfma_f32_32x32x16_bf16 v[0:15], v[148:151], v[196:199], v[0:15]
	ds_read_b64_tr_b16 v[196:197], v174 offset:5120
	ds_read_b64_tr_b16 v[198:199], v174 offset:7168
	s_waitcnt lgkmcnt(12)
	v_mfma_f32_32x32x16_bf16 v[0:15], v[152:155], v[200:203], v[0:15]
	ds_read_b64_tr_b16 v[200:201], v174 offset:9216
	ds_read_b64_tr_b16 v[202:203], v174 offset:11264
	v_mfma_f32_32x32x16_bf16 v[0:15], v[156:159], v[204:207], v[0:15]
	ds_read_b64_tr_b16 v[204:205], v174 offset:13312
	ds_read_b64_tr_b16 v[206:207], v174 offset:15360
	s_waitcnt lgkmcnt(12)
	v_mfma_f32_32x32x16_bf16 v[48:63], v[144:147], v[208:211], v[48:63]
	ds_read_b64_tr_b16 v[208:209], v174 offset:1536
	ds_read_b64_tr_b16 v[210:211], v174 offset:3584
	v_mfma_f32_32x32x16_bf16 v[48:63], v[148:151], v[212:215], v[48:63]
	ds_read_b64_tr_b16 v[212:213], v174 offset:5632
	ds_read_b64_tr_b16 v[214:215], v174 offset:7680
	s_waitcnt lgkmcnt(12)
	v_mfma_f32_32x32x16_bf16 v[48:63], v[152:155], v[216:219], v[48:63]
	ds_read_b64_tr_b16 v[216:217], v174 offset:9728
	ds_read_b64_tr_b16 v[218:219], v174 offset:11776
	v_mfma_f32_32x32x16_bf16 v[48:63], v[156:159], v[220:223], v[48:63]
	ds_read_b64_tr_b16 v[220:221], v174 offset:13824
	ds_read_b64_tr_b16 v[222:223], v174 offset:15872
	s_waitcnt lgkmcnt(12)
	v_mfma_f32_32x32x16_bf16 v[32:47], v[144:147], v[192:195], v[32:47]
	v_mfma_f32_32x32x16_bf16 v[32:47], v[148:151], v[196:199], v[32:47]
	s_waitcnt lgkmcnt(8)
	v_mfma_f32_32x32x16_bf16 v[32:47], v[152:155], v[200:203], v[32:47]
	v_mfma_f32_32x32x16_bf16 v[32:47], v[156:159], v[204:207], v[32:47]
	s_waitcnt lgkmcnt(4)
	v_mfma_f32_32x32x16_bf16 v[16:31], v[144:147], v[208:211], v[16:31]
	v_mfma_f32_32x32x16_bf16 v[16:31], v[148:151], v[212:215], v[16:31]
	s_waitcnt lgkmcnt(0)
	v_mfma_f32_32x32x16_bf16 v[16:31], v[152:155], v[216:219], v[16:31]
	v_mfma_f32_32x32x16_bf16 v[16:31], v[156:159], v[220:223], v[16:31]
	s_barrier
; #define SBAR() __builtin_amdgcn_sched_barrier(0)
; #define SLOAD(j) do { const int r0_ = TROW(j); const bf16_t* a_ = KVh + (size_t)(r0_ + sr) * LDKV + sc; const bf16_t* b_ = KVh + (size_t)(r0_ + 32 + sr) * LDKV + sc; \
;     vs0 = ld8(a_ + 128); vs1 = ld8(b_ + 128); ks0 = ld8(a_); ks1 = ld8(b_); kp0 = ld8(KPh + (size_t)(r0_ + pr) * LDKP + pc); } while (0)
; #define SWAIT() asm volatile("s_waitcnt vmcnt(0)" ::: "memory")
; __device__ __forceinline__ void partialSM(f32x16& p0, f32x16& p1, float& m_reg, float& mn, float& alpha) {
;   constexpr float C = SCALE * 1.4426950408889634f;
;   float pmax = p0[0]; for (int r = 1; r < 16; ++r) pmax = fmaxf(pmax, p0[r]); for (int r = 0; r < 16; ++r) pmax = fmaxf(pmax, p1[r]);
;   { auto rr = __builtin_amdgcn_permlane32_swap(__float_as_uint(pmax), __float_as_uint(pmax), false, false);
;     pmax = fmaxf(__uint_as_float(rr[0]), __uint_as_float(rr[1])); }
;   if (__builtin_expect(__all(pmax - m_reg <= THR / SCALE), 1)) { mn = m_reg; alpha = 1.f; }
;   else { mn = fmaxf(m_reg, pmax); alpha = __builtin_amdgcn_exp2f((m_reg - mn) * C); m_reg = mn; }
;   float mnC = -mn * C;
;   for (int r = 0; r < 16; ++r) p0[r] = fmaf(p0[r], C, mnC); for (int r = 0; r < 16; ++r) p1[r] = fmaf(p1[r], C, mnC);
;   for (int r = 0; r < 16; ++r) p0[r] = __builtin_amdgcn_exp2f(p0[r]);
; }
; __device__ __forceinline__ void finishSM(f32x16& p0, f32x16& p1, float alpha, float& l_reg, bf16x8& pa0, bf16x8& pa1, bf16x8& pa2, bf16x8& pa3) {
;   for (int r = 0; r < 16; ++r) p1[r] = __builtin_amdgcn_exp2f(p1[r]);
;   float ps = 0; for (int r = 0; r < 16; ++r) ps += p0[r]; for (int r = 0; r < 16; ++r) ps += p1[r];
; __device__ __forceinline__ void attn_unit(const bf16_t* __restrict__ Qb, const bf16_t* __restrict__ KV, const bf16_t* __restrict__ KP, bf16_t* __restrict__ Ob, ...
;     ...
;     __syncthreads(); SWAIT(); SWRITE(0);
;     RESC(alB); __syncthreads();
;     SBAR(); qkt(pA0, pA1, KN_lds, KP_lds, qr, r32, hi);
;     finishSM(pB0, pB1, alB, l_reg, pa0, pa1, pa2, pa3); SBAR();
;     SLOAD(j + 2); SBAR();
;     pv_d0(o, vb0 + SHM_V, pa0, pa1, pa2, pa3); partialSM(pA0, pA1, m_reg, mnA, alA);
;     __syncthreads(); SWAIT(); SWRITE(1);
	s_waitcnt vmcnt(0)
	ds_write_b128 v246, v[232:235]
	ds_write_b128 v247, v[236:239]
	ds_write_b128 v248, v[240:243]
	ds_write_b128 v244, v[224:227]
	ds_write_b128 v245, v[228:231]
	v_xor_b32_e32 v244, 0x4000, v244
	v_xor_b32_e32 v245, 0x4000, v245
	v_xor_b32_e32 v246, 0x4000, v246
	v_xor_b32_e32 v247, 0x4000, v247
	v_xor_b32_e32 v248, 0x2000, v248
	s_add_i32 s36, s35, 2
	s_min_u32 s36, s36, 67
	s_lshl_b32 s44, s36, 6
	s_add_i32 s45, s31, s44
	s_add_i32 s46, s24, s44
	s_add_i32 s46, s46, 0xffffff00
	s_cmp_lt_u32 s36, 4
	s_cselect_b32 s36, s45, s46
	s_add_i32 s37, s35, 1
	s_min_u32 s37, s37, 67
	s_lshl_b32 s44, s37, 6
	s_add_i32 s45, s31, s44
	s_add_i32 s46, s24, s44
	s_add_i32 s46, s46, 0xffffff00
	s_cmp_lt_u32 s37, 4
	s_cselect_b32 s37, s45, s46
	s_add_i32 s35, s35, 1
	s_lshl_b32 s44, s36, 12
	s_add_u32 s50, s47, s44
	s_addc_u32 s51, s63, 0
	s_add_u32 s52, s50, 0x20000
	s_addc_u32 s53, s51, 0
	s_lshl_b32 s44, s37, 12
	s_add_u32 s54, s47, s44
	s_addc_u32 s55, s63, 0
	s_add_u32 s56, s54, 0x20000
	s_addc_u32 s57, s55, 0
	s_lshl_b32 s44, s36, 10
	s_add_u32 s58, s60, s44
	s_addc_u32 s59, s61, 0
	global_load_dwordx4 v[232:235], v180, s[50:51]
	global_load_dwordx4 v[236:239], v180, s[52:53]
	global_load_dwordx4 v[224:227], v180, s[54:55] offset:256
	global_load_dwordx4 v[228:231], v180, s[56:57] offset:256
	global_load_dwordx4 v[240:243], v181, s[58:59]
	s_cmp_lg_u32 s62, 0
	s_cbranch_scc1 .Lpp_safe_b
	v_max3_f32 v250, v80, v81, v82
	v_max3_f32 v250, v250, v83, v84
	v_max3_f32 v250, v250, v85, v86
	v_max3_f32 v250, v250, v87, v88
	v_max3_f32 v250, v250, v89, v90
	v_max3_f32 v250, v250, v91, v92
	v_max3_f32 v250, v250, v93, v94
	v_max3_f32 v250, v250, v95, v64
	v_max3_f32 v250, v250, v65, v66
	v_max3_f32 v250, v250, v67, v68
	v_max3_f32 v250, v250, v69, v70
	v_max3_f32 v250, v250, v71, v72
	v_max3_f32 v250, v250, v73, v74
	v_max3_f32 v250, v250, v75, v76
	v_max3_f32 v250, v250, v77, v78
	v_max3_f32 v250, v250, v79, v79
	v_cmp_lt_f32_e64 vcc, s64, |v250|
	s_nop 4
	s_cbranch_vccnz .Lpp_sw_b
	v_exp_f32_e32 v80, v80
	v_exp_f32_e32 v81, v81
	v_exp_f32_e32 v82, v82
	v_exp_f32_e32 v83, v83
	v_exp_f32_e32 v84, v84
	v_exp_f32_e32 v85, v85
	v_exp_f32_e32 v86, v86
	v_exp_f32_e32 v87, v87
	v_exp_f32_e32 v88, v88
	v_exp_f32_e32 v89, v89
	v_exp_f32_e32 v90, v90
	v_exp_f32_e32 v91, v91
	v_exp_f32_e32 v92, v92
	v_exp_f32_e32 v93, v93
	v_exp_f32_e32 v94, v94
	v_exp_f32_e32 v95, v95
	v_exp_f32_e32 v64, v64
	v_exp_f32_e32 v65, v65
	v_exp_f32_e32 v66, v66
	v_exp_f32_e32 v67, v67
	v_exp_f32_e32 v68, v68
	v_exp_f32_e32 v69, v69
	v_exp_f32_e32 v70, v70
	v_exp_f32_e32 v71, v71
	v_exp_f32_e32 v72, v72
	v_exp_f32_e32 v73, v73
	v_exp_f32_e32 v74, v74
	v_exp_f32_e32 v75, v75
	v_exp_f32_e32 v76, v76
	v_exp_f32_e32 v77, v77
	v_exp_f32_e32 v78, v78
	v_exp_f32_e32 v79, v79
	s_nop 0
	v_add_f32_e32 v249, v80, v81
	v_add_f32_e32 v249, v82, v249
	v_add_f32_e32 v249, v83, v249
	v_add_f32_e32 v249, v84, v249
	v_add_f32_e32 v249, v85, v249
	v_add_f32_e32 v249, v86, v249
	v_add_f32_e32 v249, v87, v249
	v_add_f32_e32 v249, v88, v249
	v_add_f32_e32 v249, v89, v249
	v_add_f32_e32 v249, v90, v249
	v_add_f32_e32 v249, v91, v249
	v_add_f32_e32 v249, v92, v249
	v_add_f32_e32 v249, v93, v249
	v_add_f32_e32 v249, v94, v249
	v_add_f32_e32 v249, v95, v249
	v_add_f32_e32 v249, v64, v249
	v_add_f32_e32 v249, v65, v249
	v_add_f32_e32 v249, v66, v249
	v_add_f32_e32 v249, v67, v249
	v_add_f32_e32 v249, v68, v249
	v_add_f32_e32 v249, v69, v249
	v_add_f32_e32 v249, v70, v249
	v_add_f32_e32 v249, v71, v249
	v_add_f32_e32 v249, v72, v249
	v_add_f32_e32 v249, v73, v249
	v_add_f32_e32 v249, v74, v249
	v_add_f32_e32 v249, v75, v249
	v_add_f32_e32 v249, v76, v249
	v_add_f32_e32 v249, v77, v249
	v_add_f32_e32 v249, v78, v249
	v_add_f32_e32 v249, v79, v249
	v_add_f32_e32 v176, v176, v249
	v_cvt_pk_bf16_f32 v144, v80, v81
	v_cvt_pk_bf16_f32 v145, v82, v83
	v_cvt_pk_bf16_f32 v146, v84, v85
	v_cvt_pk_bf16_f32 v147, v86, v87
	v_cvt_pk_bf16_f32 v148, v88, v89
	v_cvt_pk_bf16_f32 v149, v90, v91
	v_cvt_pk_bf16_f32 v150, v92, v93
	v_cvt_pk_bf16_f32 v151, v94, v95
	v_cvt_pk_bf16_f32 v152, v64, v65
	v_cvt_pk_bf16_f32 v153, v66, v67
	v_cvt_pk_bf16_f32 v154, v68, v69
	v_cvt_pk_bf16_f32 v155, v70, v71
	v_cvt_pk_bf16_f32 v156, v72, v73
	v_cvt_pk_bf16_f32 v157, v74, v75
	v_cvt_pk_bf16_f32 v158, v76, v77
	v_cvt_pk_bf16_f32 v159, v78, v79
	s_nop 1
	v_permlane32_swap_b32_e32 v144, v146
	v_permlane32_swap_b32_e32 v145, v147
	v_permlane32_swap_b32_e32 v148, v150
	v_permlane32_swap_b32_e32 v149, v151
	v_permlane32_swap_b32_e32 v152, v154
	v_permlane32_swap_b32_e32 v153, v155
	v_permlane32_swap_b32_e32 v156, v158
	v_permlane32_swap_b32_e32 v157, v159
	s_branch .Lpp_send_b

; __device__ __forceinline__ void qkt(f32x16& p0, f32x16& p1, const char* Kn, const char* Kp, const bf16x8* qr, int r32, int hi) {
;   p0 = f32x16{}; p1 = f32x16{};
; #pragma unroll
;   for (int d0 = 0; d0 < 8; ++d0) { int cb = (d0 * 16 + hi * 8) * 2;
;     bf16x8 b0 = *reinterpret_cast<const bf16x8*>(Kn + KSWZ(r32, cb));
;     bf16x8 b1 = *reinterpret_cast<const bf16x8*>(Kn + KSWZ(32 + r32, cb));
;     p0 = __builtin_amdgcn_mfma_f32_32x32x16_bf16(b0, qr[d0], p0, 0, 0, 0);
;     p1 = __builtin_amdgcn_mfma_f32_32x32x16_bf16(b1, qr[d0], p1, 0, 0, 0); }
; #pragma unroll
;   for (int d1 = 0; d1 < 4; ++d1) { int cb = (d1 * 16 + hi * 8) * 2;
;     bf16x8 b0 = *reinterpret_cast<const bf16x8*>(Kp + KPSWZ(r32, cb));
;     bf16x8 b1 = *reinterpret_cast<const bf16x8*>(Kp + KPSWZ(32 + r32, cb));
;     p0 = __builtin_amdgcn_mfma_f32_32x32x16_bf16(b0, qr[8 + d1], p0, 0, 0, 0);
;     p1 = __builtin_amdgcn_mfma_f32_32x32x16_bf16(b1, qr[8 + d1], p1, 0, 0, 0); }
; }
; __device__ __forceinline__ int v_st(int k, int c) { const int kk = (k & ~0xC) | ((k & 4) << 1) | ((k & 8) >> 1); return ((kk >> 3) * 4 + (c >> 5)) * 512 + ((kk & 7) * 32 + (c & 31)) * 2; }
; __device__ __forceinline__ int v_rd_base(int lane) { return ((lane & 3) << 3) | (((lane >> 2) & 3) << 6) | (((lane >> 4) & 1) << 5) | (((lane >> 5) & 1) << 8); }
; template <int OFF> __device__ __forceinline__ s16x4 tr_read(int vb) {
;   s16x4 r; asm volatile("ds_read_b64_tr_b16 %0, %1 offset:%2" : "=&v"(r) : "v"(vb), "i"(OFF) : "memory"); return r;
; }
; template <int D0> __device__ __forceinline__ void pv_one(f32x16& od, int vb, bf16x8 pa0, bf16x8 pa1, bf16x8 pa2, bf16x8 pa3) {
;   const s16x4 l0 = tr_read<v_rd_off(D0, 0, 0)>(vb), h0 = tr_read<v_rd_off(D0, 0, 1)>(vb), l1 = tr_read<v_rd_off(D0, 1, 0)>(vb), h1 = tr_read<v_rd_off(D0, 1, 1)>(vb);
;   const s16x4 l2 = tr_read<v_rd_off(D0, 2, 0)>(vb), h2 = tr_read<v_rd_off(D0, 2, 1)>(vb), l3 = tr_read<v_rd_off(D0, 3, 0)>(vb), h3 = tr_read<v_rd_off(D0, 3, 1)>(vb);
;   asm volatile("s_waitcnt lgkmcnt(0)" ::: "memory"); SBAR();
;     ...
;   od = __builtin_amdgcn_mfma_f32_32x32x16_bf16(pa0, PK(l0, h0), od, 0, 0, 0);
;   od = __builtin_amdgcn_mfma_f32_32x32x16_bf16(pa1, PK(l1, h1), od, 0, 0, 0);
;   od = __builtin_amdgcn_mfma_f32_32x32x16_bf16(pa2, PK(l2, h2), od, 0, 0, 0);
;   od = __builtin_amdgcn_mfma_f32_32x32x16_bf16(pa3, PK(l3, h3), od, 0, 0, 0);
;     ...
; }
.Lpp_send_b:
	s_waitcnt lgkmcnt(0)
	s_barrier
	s_add_i32 s11, s11, 1
	s_cmp_eq_u32 s11, 68
	s_cbranch_scc1 .Lpp_last
	ds_read_b128 v[192:195], v160
	ds_read_b128 v[196:199], v160 offset:8192
	ds_read_b128 v[200:203], v161
	ds_read_b128 v[204:207], v161 offset:8192
	ds_read_b128 v[208:211], v162
	ds_read_b128 v[212:215], v162 offset:8192
	ds_read_b128 v[216:219], v163
	ds_read_b128 v[220:223], v163 offset:8192
	s_waitcnt lgkmcnt(6)
	v_mfma_f32_32x32x16_bf16 v[80:95], v[192:195], v[136:139], 0
	ds_read_b128 v[192:195], v164
	v_mfma_f32_32x32x16_bf16 v[64:79], v[196:199], v[136:139], 0
	ds_read_b128 v[196:199], v164 offset:8192
	s_waitcnt lgkmcnt(6)
	v_mfma_f32_32x32x16_bf16 v[80:95], v[200:203], v[132:135], v[80:95]
	ds_read_b128 v[200:203], v165
	v_mfma_f32_32x32x16_bf16 v[64:79], v[204:207], v[132:135], v[64:79]
	ds_read_b128 v[204:207], v165 offset:8192
	s_waitcnt lgkmcnt(6)
	v_mfma_f32_32x32x16_bf16 v[80:95], v[208:211], v[128:131], v[80:95]
	ds_read_b128 v[208:211], v166
	v_mfma_f32_32x32x16_bf16 v[64:79], v[212:215], v[128:131], v[64:79]
	ds_read_b128 v[212:215], v166 offset:8192
	s_waitcnt lgkmcnt(6)
	v_mfma_f32_32x32x16_bf16 v[80:95], v[216:219], v[124:127], v[80:95]
	ds_read_b128 v[216:219], v167
	v_mfma_f32_32x32x16_bf16 v[64:79], v[220:223], v[124:127], v[64:79]
	ds_read_b128 v[220:223], v167 offset:8192
	s_waitcnt lgkmcnt(6)
	v_mfma_f32_32x32x16_bf16 v[80:95], v[192:195], v[120:123], v[80:95]
	ds_read_b128 v[192:195], v168
	v_mfma_f32_32x32x16_bf16 v[64:79], v[196:199], v[120:123], v[64:79]
	ds_read_b128 v[196:199], v168 offset:4096
	s_waitcnt lgkmcnt(6)
	v_mfma_f32_32x32x16_bf16 v[80:95], v[200:203], v[140:143], v[80:95]
	ds_read_b128 v[200:203], v169
	v_mfma_f32_32x32x16_bf16 v[64:79], v[204:207], v[140:143], v[64:79]
	ds_read_b128 v[204:207], v169 offset:4096
	s_waitcnt lgkmcnt(6)
	v_mfma_f32_32x32x16_bf16 v[80:95], v[208:211], v[116:119], v[80:95]
	ds_read_b128 v[208:211], v170
	v_mfma_f32_32x32x16_bf16 v[64:79], v[212:215], v[116:119], v[64:79]
	ds_read_b128 v[212:215], v170 offset:4096
	s_waitcnt lgkmcnt(6)
	v_mfma_f32_32x32x16_bf16 v[80:95], v[216:219], v[112:115], v[80:95]
	ds_read_b128 v[216:219], v171
	v_mfma_f32_32x32x16_bf16 v[64:79], v[220:223], v[112:115], v[64:79]
	ds_read_b128 v[220:223], v171 offset:4096
	s_waitcnt lgkmcnt(6)
	v_mfma_f32_32x32x16_bf16 v[80:95], v[192:195], v[108:111], v[80:95]
	ds_read_b64_tr_b16 v[192:193], v174 offset:16384
	ds_read_b64_tr_b16 v[194:195], v174 offset:18432
	v_mfma_f32_32x32x16_bf16 v[64:79], v[196:199], v[108:111], v[64:79]
	ds_read_b64_tr_b16 v[196:197], v174 offset:20480
	ds_read_b64_tr_b16 v[198:199], v174 offset:22528
	s_waitcnt lgkmcnt(8)
	v_mfma_f32_32x32x16_bf16 v[80:95], v[200:203], v[104:107], v[80:95]
	ds_read_b64_tr_b16 v[200:201], v174 offset:24576
	ds_read_b64_tr_b16 v[202:203], v174 offset:26624
	v_mfma_f32_32x32x16_bf16 v[64:79], v[204:207], v[104:107], v[64:79]
	ds_read_b64_tr_b16 v[204:205], v174 offset:28672
	ds_read_b64_tr_b16 v[206:207], v174 offset:30720
	s_waitcnt lgkmcnt(10)
	v_mfma_f32_32x32x16_bf16 v[80:95], v[208:211], v[100:103], v[80:95]
	ds_read_b64_tr_b16 v[208:209], v174 offset:16896
	ds_read_b64_tr_b16 v[210:211], v174 offset:18944
	v_mfma_f32_32x32x16_bf16 v[64:79], v[212:215], v[100:103], v[64:79]
	ds_read_b64_tr_b16 v[212:213], v174 offset:20992
	ds_read_b64_tr_b16 v[214:215], v174 offset:23040
	s_waitcnt lgkmcnt(12)
	v_mfma_f32_32x32x16_bf16 v[80:95], v[216:219], v[96:99], v[80:95]
	ds_read_b64_tr_b16 v[216:217], v174 offset:25088
	ds_read_b64_tr_b16 v[218:219], v174 offset:27136
	v_mfma_f32_32x32x16_bf16 v[64:79], v[220:223], v[96:99], v[64:79]
	ds_read_b64_tr_b16 v[220:221], v174 offset:29184
	ds_read_b64_tr_b16 v[222:223], v174 offset:31232
	s_waitcnt lgkmcnt(12)
	v_mfma_f32_32x32x16_bf16 v[0:15], v[144:147], v[192:195], v[0:15]
	ds_read_b64_tr_b16 v[192:193], v174 offset:17408
	ds_read_b64_tr_b16 v[194:195], v174 offset:19456
	v_mfma_f32_32x32x16_bf16 v[0:15], v[148:151], v[196:199], v[0:15]
	ds_read_b64_tr_b16 v[196:197], v174 offset:21504
	ds_read_b64_tr_b16 v[198:199], v174 offset:23552
	s_waitcnt lgkmcnt(12)
	v_mfma_f32_32x32x16_bf16 v[0:15], v[152:155], v[200:203], v[0:15]
	ds_read_b64_tr_b16 v[200:201], v174 offset:25600
	ds_read_b64_tr_b16 v[202:203], v174 offset:27648
	v_mfma_f32_32x32x16_bf16 v[0:15], v[156:159], v[204:207], v[0:15]
	ds_read_b64_tr_b16 v[204:205], v174 offset:29696
	ds_read_b64_tr_b16 v[206:207], v174 offset:31744
	s_waitcnt lgkmcnt(12)
	v_mfma_f32_32x32x16_bf16 v[48:63], v[144:147], v[208:211], v[48:63]
	ds_read_b64_tr_b16 v[208:209], v174 offset:17920
	ds_read_b64_tr_b16 v[210:211], v174 offset:19968
	v_mfma_f32_32x32x16_bf16 v[48:63], v[148:151], v[212:215], v[48:63]
	ds_read_b64_tr_b16 v[212:213], v174 offset:22016
	ds_read_b64_tr_b16 v[214:215], v174 offset:24064
	s_waitcnt lgkmcnt(12)
	v_mfma_f32_32x32x16_bf16 v[48:63], v[152:155], v[216:219], v[48:63]
	ds_read_b64_tr_b16 v[216:217], v174 offset:26112
	ds_read_b64_tr_b16 v[218:219], v174 offset:28160
	v_mfma_f32_32x32x16_bf16 v[48:63], v[156:159], v[220:223], v[48:63]
	ds_read_b64_tr_b16 v[220:221], v174 offset:30208
	ds_read_b64_tr_b16 v[222:223], v174 offset:32256
	s_waitcnt lgkmcnt(12)
	v_mfma_f32_32x32x16_bf16 v[32:47], v[144:147], v[192:195], v[32:47]
	v_mfma_f32_32x32x16_bf16 v[32:47], v[148:151], v[196:199], v[32:47]
	s_waitcnt lgkmcnt(8)
	v_mfma_f32_32x32x16_bf16 v[32:47], v[152:155], v[200:203], v[32:47]
	v_mfma_f32_32x32x16_bf16 v[32:47], v[156:159], v[204:207], v[32:47]
	s_waitcnt lgkmcnt(4)
	v_mfma_f32_32x32x16_bf16 v[16:31], v[144:147], v[208:211], v[16:31]
	v_mfma_f32_32x32x16_bf16 v[16:31], v[148:151], v[212:215], v[16:31]
	s_waitcnt lgkmcnt(0)
	v_mfma_f32_32x32x16_bf16 v[16:31], v[152:155], v[216:219], v[16:31]
	v_mfma_f32_32x32x16_bf16 v[16:31], v[156:159], v[220:223], v[16:31]
	s_barrier
	s_branch .Lpp_loop
; #define SBAR() __builtin_amdgcn_sched_barrier(0)
; template <int D0> __device__ __forceinline__ void pv_one(f32x16& od, int vb, bf16x8 pa0, bf16x8 pa1, bf16x8 pa2, bf16x8 pa3) {
;   const s16x4 l0 = tr_read<v_rd_off(D0, 0, 0)>(vb), h0 = tr_read<v_rd_off(D0, 0, 1)>(vb), l1 = tr_read<v_rd_off(D0, 1, 0)>(vb), h1 = tr_read<v_rd_off(D0, 1, 1)>(vb);
;   const s16x4 l2 = tr_read<v_rd_off(D0, 2, 0)>(vb), h2 = tr_read<v_rd_off(D0, 2, 1)>(vb), l3 = tr_read<v_rd_off(D0, 3, 0)>(vb), h3 = tr_read<v_rd_off(D0, 3, 1)>(vb);
;   asm volatile("s_waitcnt lgkmcnt(0)" ::: "memory"); SBAR();
;     ...
;   od = __builtin_amdgcn_mfma_f32_32x32x16_bf16(pa0, PK(l0, h0), od, 0, 0, 0);
;   od = __builtin_amdgcn_mfma_f32_32x32x16_bf16(pa1, PK(l1, h1), od, 0, 0, 0);
;   od = __builtin_amdgcn_mfma_f32_32x32x16_bf16(pa2, PK(l2, h2), od, 0, 0, 0);
;   od = __builtin_amdgcn_mfma_f32_32x32x16_bf16(pa3, PK(l3, h3), od, 0, 0, 0);
;     ...
; }
; __device__ __forceinline__ void pv_d0(f32x16* o, int vb, bf16x8 pa0, bf16x8 pa1, bf16x8 pa2, bf16x8 pa3) {
;   pv_one<0>(o[0], vb, pa0, pa1, pa2, pa3); pv_one<1>(o[1], vb, pa0, pa1, pa2, pa3); pv_one<2>(o[2], vb, pa0, pa1, pa2, pa3); pv_one<3>(o[3], vb, pa0, pa1, pa2, pa3);
; __device__ __forceinline__ void attn_unit(const bf16_t* __restrict__ Qb, const bf16_t* __restrict__ KV, const bf16_t* __restrict__ KP, bf16_t* __restrict__ Ob, ...
;     ...
;   finishSM(pB0, pB1, alB, l_reg, pa0, pa1, pa2, pa3); SBAR();
;   pv_d0(o, vb0 + SHM_V, pa0, pa1, pa2, pa3);
;   if (hi == 0) li_l[r32] = l_reg; asm volatile("s_waitcnt lgkmcnt(0)" ::: "memory");
.Lpp_last:
	ds_read_b64_tr_b16 v[192:193], v174 offset:16384
	ds_read_b64_tr_b16 v[194:195], v174 offset:18432
	ds_read_b64_tr_b16 v[196:197], v174 offset:20480
	ds_read_b64_tr_b16 v[198:199], v174 offset:22528
	ds_read_b64_tr_b16 v[200:201], v174 offset:24576
	ds_read_b64_tr_b16 v[202:203], v174 offset:26624
	ds_read_b64_tr_b16 v[204:205], v174 offset:28672
	ds_read_b64_tr_b16 v[206:207], v174 offset:30720
	ds_read_b64_tr_b16 v[208:209], v174 offset:16896
	ds_read_b64_tr_b16 v[210:211], v174 offset:18944
	ds_read_b64_tr_b16 v[212:213], v174 offset:20992
	ds_read_b64_tr_b16 v[214:215], v174 offset:23040
	ds_read_b64_tr_b16 v[216:217], v174 offset:25088
	ds_read_b64_tr_b16 v[218:219], v174 offset:27136
	ds_read_b64_tr_b16 v[220:221], v174 offset:29184
	ds_read_b64_tr_b16 v[222:223], v174 offset:31232
	s_waitcnt lgkmcnt(12)
	s_nop 0
	v_mfma_f32_32x32x16_bf16 v[0:15], v[144:147], v[192:195], v[0:15]
	ds_read_b64_tr_b16 v[192:193], v174 offset:17408
	ds_read_b64_tr_b16 v[194:195], v174 offset:19456
	v_mfma_f32_32x32x16_bf16 v[0:15], v[148:151], v[196:199], v[0:15]
	ds_read_b64_tr_b16 v[196:197], v174 offset:21504
	ds_read_b64_tr_b16 v[198:199], v174 offset:23552
	s_waitcnt lgkmcnt(12)
	v_mfma_f32_32x32x16_bf16 v[0:15], v[152:155], v[200:203], v[0:15]
	ds_read_b64_tr_b16 v[200:201], v174 offset:25600
	ds_read_b64_tr_b16 v[202:203], v174 offset:27648
	v_mfma_f32_32x32x16_bf16 v[0:15], v[156:159], v[204:207], v[0:15]
	ds_read_b64_tr_b16 v[204:205], v174 offset:29696
	ds_read_b64_tr_b16 v[206:207], v174 offset:31744
	s_waitcnt lgkmcnt(12)
	v_mfma_f32_32x32x16_bf16 v[48:63], v[144:147], v[208:211], v[48:63]
	ds_read_b64_tr_b16 v[208:209], v174 offset:17920
	ds_read_b64_tr_b16 v[210:211], v174 offset:19968
	v_mfma_f32_32x32x16_bf16 v[48:63], v[148:151], v[212:215], v[48:63]
	ds_read_b64_tr_b16 v[212:213], v174 offset:22016
	ds_read_b64_tr_b16 v[214:215], v174 offset:24064
	s_waitcnt lgkmcnt(12)
	v_mfma_f32_32x32x16_bf16 v[48:63], v[152:155], v[216:219], v[48:63]
	ds_read_b64_tr_b16 v[216:217], v174 offset:26112
	ds_read_b64_tr_b16 v[218:219], v174 offset:28160
	v_mfma_f32_32x32x16_bf16 v[48:63], v[156:159], v[220:223], v[48:63]
	ds_read_b64_tr_b16 v[220:221], v174 offset:30208
	ds_read_b64_tr_b16 v[222:223], v174 offset:32256
	s_waitcnt lgkmcnt(12)
	v_mfma_f32_32x32x16_bf16 v[32:47], v[144:147], v[192:195], v[32:47]
	v_mfma_f32_32x32x16_bf16 v[32:47], v[148:151], v[196:199], v[32:47]
	s_waitcnt lgkmcnt(8)
	v_mfma_f32_32x32x16_bf16 v[32:47], v[152:155], v[200:203], v[32:47]
	v_mfma_f32_32x32x16_bf16 v[32:47], v[156:159], v[204:207], v[32:47]
	s_waitcnt lgkmcnt(4)
	v_mfma_f32_32x32x16_bf16 v[16:31], v[144:147], v[208:211], v[16:31]
	v_mfma_f32_32x32x16_bf16 v[16:31], v[148:151], v[212:215], v[16:31]
	s_waitcnt lgkmcnt(0)
	v_mfma_f32_32x32x16_bf16 v[16:31], v[152:155], v[216:219], v[16:31]
	v_mfma_f32_32x32x16_bf16 v[16:31], v[156:159], v[220:223], v[16:31]
	s_barrier
	s_cmp_lg_u32 s41, 0
	s_cbranch_scc1 .Lpp_fin
	s_barrier
.Lpp_fin:
	s_waitcnt vmcnt(0)
	s_cmp_lg_u32 s62, 0
	s_cbranch_scc1 .Lpp_lok
	v_mov_b32_e32 v250, v176
	s_nop 1
	v_permlane32_swap_b32_e32 v176, v250
	v_add_f32_e32 v176, v176, v250
.Lpp_lok:
	s_and_saveexec_b64 s[8:9], s[6:7]
	ds_write_b32 v186, v176
	s_branch .LBB0_1451
